# v18: v11 + dead Xb stores of FFN1out-L0 / FFN2out-L1 epilogues removed + phase-0 sample-K conversion enumerates only needed rows
# speedup vs baseline: 1.1666x; 1.0067x over previous
_Z8yoco_fwd6Params:
	s_load_dwordx16 s[12:27], s[0:1], 0x0
	s_load_dwordx16 s[36:51], s[0:1], 0x40
	s_load_dwordx16 s[52:67], s[0:1], 0x80
	s_load_dwordx8 s[68:75], s[0:1], 0xc0
	s_load_dword s78, s[0:1], 0xe0
	v_and_b32_e32 v174, 0x3ff, v0
	s_add_u32 s8, s0, 0xe0
	v_mov_b32_e32 v70, v174
	s_addc_u32 s9, s1, 0
	s_lshl_b32 s33, s2, 3
	v_ashrrev_i32_e32 v67, 6, v70
	s_movk_i32 s0, 0x2100
	v_and_b32_e32 v66, 63, v70
	v_add_u32_e32 v68, s33, v67
	v_mul_lo_u32 v1, v67, s0
	s_movk_i32 s0, 0x5000
	s_mov_b32 s79, 0
	s_waitcnt lgkmcnt(0)
	v_mov_b32_e32 v235, s18
	v_mov_b32_e32 v236, s19
	v_mov_b32_e32 v237, s20
	v_mov_b32_e32 v238, s21
	v_mov_b32_e32 v239, s72
	v_mov_b32_e32 v240, s73
	s_lshl_b32 s76, s78, 3
	v_ashrrev_i32_e32 v71, 31, v70
	v_add_u32_e32 v124, 0, v1
	v_cmp_gt_i32_e32 vcc, s0, v68
	v_lshrrev_b32_e32 v1, 3, v66
	v_lshlrev_b32_e32 v72, 3, v66
	v_mov_b32_e32 v110, v68
	s_and_saveexec_b64 s[10:11], vcc
	s_cbranch_execz .LBB0_96
	v_and_b32_e32 v80, 56, v72
	v_lshrrev_b32_e32 v76, 5, v66
	v_mul_u32_u24_e32 v3, 0x84, v80
	v_lshlrev_b32_e32 v6, 2, v1
	s_movk_i32 s3, 0x84
	v_add3_u32 v79, v124, v3, v6
	v_or_b32_e32 v127, 2, v76
	v_mov_b32_e32 v3, 0x108
	v_mad_u32_u24 v130, v127, s3, v3
	v_mov_b32_e32 v3, 0x318
	v_mad_u32_u24 v132, v127, s3, v3
	v_mov_b32_e32 v3, 0x528
	v_mad_u32_u24 v133, v127, s3, v3
	v_mov_b32_e32 v3, 0x630
	v_mad_u32_u24 v6, v127, s3, v3
	v_mov_b32_e32 v3, 0x738
	v_mad_u32_u24 v134, v127, s3, v3
	v_mov_b32_e32 v3, 0x948
	v_mad_u32_u24 v135, v127, s3, v3
	v_mov_b32_e32 v3, 0xb58
	v_mad_u32_u24 v136, v127, s3, v3
	v_mov_b32_e32 v3, 0xc60
	v_mad_u32_u24 v7, v127, s3, v3
	v_mov_b32_e32 v3, 0xd68
	v_mad_u32_u24 v137, v127, s3, v3
	v_mov_b32_e32 v3, 0xf78
	v_mad_u32_u24 v138, v127, s3, v3
	v_mov_b32_e32 v3, 0x1188
	v_mad_u32_u24 v139, v127, s3, v3
	v_mov_b32_e32 v3, 0x1290
	v_mov_b32_e32 v75, 0
	v_and_b32_e32 v78, 31, v70
	v_mad_u32_u24 v8, v127, s3, v3
	v_mov_b32_e32 v3, 0x1398
	v_lshlrev_b32_e32 v2, 2, v78
	v_lshlrev_b32_e32 v74, 1, v80
	v_mad_u32_u24 v140, v127, s3, v3
	v_mov_b32_e32 v3, v75
	v_add_u32_e32 v69, v124, v2
	v_lshl_add_u64 v[4:5], s[74:75], 0, v[74:75]
	s_mov_b64 s[0:1], 0x4f00000
	v_lshl_add_u64 v[90:91], s[68:69], 0, v[2:3]
	v_lshl_add_u64 v[92:93], s[66:67], 0, v[2:3]
	v_lshl_add_u64 v[94:95], s[64:65], 0, v[2:3]
	v_lshl_add_u64 v[96:97], s[60:61], 0, v[2:3]
	v_lshlrev_b32_e32 v2, 1, v67
	v_lshl_add_u64 v[82:83], v[4:5], 0, s[0:1]
	s_mov_b64 s[0:1], 0x4c00000
	s_add_u32 s28, s42, 0x1000
	v_lshl_add_u32 v141, s2, 4, v2
	v_lshlrev_b32_e32 v2, 5, v67
	v_lshl_add_u64 v[84:85], v[4:5], 0, s[0:1]
	s_mov_b64 s[0:1], 0x4600000
	s_addc_u32 s29, s43, 0
	v_lshl_add_u32 v142, s2, 8, v2
	v_lshlrev_b32_e32 v2, 8, v67
	v_lshl_add_u64 v[86:87], v[4:5], 0, s[0:1]
	s_mov_b64 s[0:1], 0x4200000
	s_cmp_lg_u64 s[62:63], 0
	v_lshl_add_u32 v143, s2, 11, v2
	v_lshlrev_b32_e32 v2, 4, v67
	v_mad_u32_u24 v73, v76, s3, v69
	v_or_b32_e32 v81, 8, v1
	v_or_b32_e32 v125, 16, v1
	v_or_b32_e32 v126, 24, v1
	v_mul_u32_u24_e32 v128, 0x84, v127
	v_or_b32_e32 v129, 4, v76
	v_or_b32_e32 v131, 6, v76
	v_lshl_add_u64 v[88:89], v[4:5], 0, s[0:1]
	s_cselect_b64 s[30:31], -1, 0
	v_mov_b32_e32 v77, v75
	s_lshl_b32 s3, s78, 4
	s_lshl_b32 s77, s78, 8
	s_lshl_b32 s84, s78, 11
	v_lshl_add_u32 v144, s2, 7, v2
	s_lshl_b32 s85, s78, 7
	s_mov_b32 s86, 0x0
	s_mov_b32 s87, 0x2ad5802b
	s_movk_i32 s88, 0x5fa
	s_mov_b32 s93, 0x18000
	s_mov_b32 s95, 0x24000
	v_or_b32_e32 v145, 8, v76
	v_or_b32_e32 v146, 10, v76
	v_or_b32_e32 v147, 12, v76
	s_mov_b32 s97, 0x30000
	v_or_b32_e32 v148, 14, v76
	v_or_b32_e32 v149, 16, v76
	v_or_b32_e32 v150, 18, v76
	v_or_b32_e32 v151, 20, v76
	s_mov_b32 s91, 0x3c000
	v_or_b32_e32 v152, 22, v76
	v_or_b32_e32 v153, 24, v76
	v_or_b32_e32 v154, 26, v76
	v_or_b32_e32 v155, 28, v76
	s_mov_b32 s94, 0x48000
	v_or_b32_e32 v156, 30, v76
	v_or_b32_e32 v157, 32, v76
	v_or_b32_e32 v158, 34, v76
	v_or_b32_e32 v159, 36, v76
	v_or_b32_e32 v160, 38, v76
	v_or_b32_e32 v161, 40, v76
	v_or_b32_e32 v162, 42, v76
	v_add_u32_e32 v163, v69, v6
	v_add_u32_e32 v164, v69, v7
	v_add_u32_e32 v165, v69, v8
	v_or_b32_e32 v166, 44, v76
	v_or_b32_e32 v167, 46, v76
	v_or_b32_e32 v168, 48, v76
	v_or_b32_e32 v169, 50, v76
	v_or_b32_e32 v170, 52, v76
	v_or_b32_e32 v171, 54, v76
	v_or_b32_e32 v172, 56, v76
	v_or_b32_e32 v173, 58, v76
	v_or_b32_e32 v175, 60, v76
	v_or_b32_e32 v176, 62, v76
	v_add_u32_e32 v177, s76, v67
	v_mov_b32_e32 v178, 0x3700000
	v_mov_b32_e32 v179, 0x2c00000
	v_mov_b32_e32 v180, 6
	v_mov_b32_e32 v181, 5
	v_mov_b32_e32 v182, 0x1600000
	v_mov_b32_e32 v183, 0x1f210000
	v_mov_b32_e32 v184, 0x7210000
	v_mov_b32_e32 v185, v67
	v_mov_b32_e32 v186, v67
	s_mov_b32 s90, 0x54000
	s_mov_b32 s92, 0xb00000
	s_mov_b32 s96, 0x2e8ba2e9
	s_movk_i32 s89, 0x5800
	s_mov_b64 s[34:35], 0
	s_mov_b64 s[60:61], 0xc000
	s_branch .LBB0_3

.LBB0_96:
	s_or_b64 exec, exec, s[10:11]
	s_add_u32 s38, s74, 0x5000000
	s_addc_u32 s39, s75, 0
	s_add_u32 s40, s74, 0x9100000
	s_addc_u32 s41, s75, 0
	s_add_u32 s6, s74, 0x12b60000
	s_movk_i32 s0, 0x4100
	s_addc_u32 s7, s75, 0
	v_cmp_gt_i32_e32 vcc, s0, v68
	v_mbcnt_lo_u32_b32 v175, -1, 0
	s_and_saveexec_b64 s[10:11], vcc
	s_cbranch_execz .LBB0_108
	s_waitcnt vmcnt(1)
	v_mov_b32_e32 v35, 0
	v_ashrrev_i32_e32 v69, 31, v68
	v_lshlrev_b32_e32 v34, 4, v66
	v_mov_b32_e32 v73, v35
	s_ashr_i32 s77, s76, 31
	v_lshlrev_b64 v[2:3], 12, v[68:69]
	v_cmp_eq_u32_e64 s[0:1], 0, v66
	v_lshl_add_u64 v[36:37], s[38:39], 0, v[34:35]
	v_lshl_add_u64 v[38:39], s[40:41], 0, v[72:73]
	v_lshlrev_b32_e32 v48, 9, v110
	s_lshl_b32 s3, s76, 9
	v_lshl_add_u64 v[40:41], s[12:13], 0, v[2:3]
	s_lshl_b64 s[22:23], s[76:77], 12
	s_mov_b64 s[12:13], 0
	s_mov_b32 s28, 0x0
	s_mov_b32 s29, 0x2ad5802b
	s_movk_i32 s30, 0x5fa
	s_mov_b64 s[24:25], 0xc000
	s_movk_i32 s31, 0x3fff
	v_mbcnt_hi_u32_b32 v49, -1, v175
	s_movk_i32 s34, 0x40ff
	v_lshlrev_b32_e32 v34, 4, v66
	v_mov_b32_e32 v50, 0x1f210000
	v_mov_b32_e32 v51, 0x7210000
	v_mov_b64_e32 v[42:43], v[68:69]
	s_branch .LBB0_99

.LBB0_135:
	s_or_b64 exec, exec, s[4:5]
	s_add_u32 s48, s74, 0x1c665c00
	s_mov_b32 s0, 0xc00000
	s_addc_u32 s49, s75, 0
	v_cmp_gt_u32_e32 vcc, s0, v2
	v_lshlrev_b32_e32 v3, 3, v70
	s_and_saveexec_b64 s[0:1], vcc
	s_cbranch_execz .LBB0_148
	v_lshrrev_b32_e32 v71, 6, v174
	v_and_b32_e32 v72, 63, v174
	v_and_b32_e32 v73, 7, v72
	v_lshrrev_b32_e32 v74, 3, v72
	v_readfirstlane_b32 s80, v71
	s_add_i32 s80, s80, s33
	s_lshl_b32 s80, s80, 3
	v_lshlrev_b32_e32 v75, 8, v74
	v_lshl_add_u32 v75, v73, 5, v75
	v_mul_u32_u24_e32 v76, 0x44000, v74
	v_lshl_add_u32 v76, v73, 4, v76
	s_mov_b32 s81, 0
.Lg1_loop:
	s_add_i32 s82, s81, 0
	s_lshl_b32 s82, s82, 14
	s_add_i32 s82, s82, s80
	s_lshr_b32 s83, s82, 10
	s_mul_i32 s83, s83, 0x4ec5
	s_lshr_b32 s83, s83, 18
	s_mul_i32 s84, s83, 0x3400
	s_sub_i32 s84, s82, s84
	s_movk_i32 s85, 0x1400
	s_movk_i32 s86, 4
	s_cmpk_lt_u32 s84, 0x1400
	s_cselect_b32 s85, 0x400, s85
	s_cselect_b32 s86, 2, s86
	s_cselect_b32 s87, 1, 0
	s_movk_i32 s88, 0x600
	s_cmpk_lt_u32 s84, 0x400
	s_cselect_b32 s85, 0, s85
	s_cselect_b32 s86, 0, s86
	s_cselect_b32 s88, 0x780, s88
	s_sub_i32 s85, s84, s85
	s_lshr_b32 s85, s85, 3
	s_add_i32 s88, s88, s85
	s_lshr_b32 s89, s85, 3
	s_lshl_b32 s89, s89, 4
	s_and_b32 s90, s85, 7
	s_add_i32 s89, s89, s90
	s_cmp_eq_u32 s87, 1
	s_cselect_b32 s88, s88, s89
	s_lshl_b32 s89, 1, s86
	s_add_i32 s89, s89, -1
	s_and_b32 s89, s88, s89
	s_lshr_b32 s90, s88, s86
	s_lshr_b32 s91, 0x800, s86
	s_add_i32 s91, s91, 8
	s_mul_i32 s89, s89, s91
	s_add_i32 s89, s89, s90
	s_lshl_b32 s90, s86, 2
	s_mul_i32 s91, s83, 24
	s_add_i32 s91, s91, s90
	s_mul_i32 s91, s91, 0x880
	s_add_i32 s91, s91, s89
	s_lshl_b32 s91, s91, 7
	s_lshl_b32 s89, s83, 11
	s_add_i32 s89, s89, s88
	s_mul_i32 s89, s89, 0x1800
	s_lshl_b32 s90, s90, 8
	s_add_i32 s89, s89, s90
	v_add_u32_e32 v77, s89, v75
	v_add_u32_e32 v78, s91, v76
	global_load_dwordx4 v[80:83], v77, s[18:19]
	global_load_dwordx4 v[84:87], v77, s[18:19] offset:16
	s_add_i32 s82, s81, 1
	s_lshl_b32 s82, s82, 14
	s_add_i32 s82, s82, s80
	s_lshr_b32 s83, s82, 10
	s_mul_i32 s83, s83, 0x4ec5
	s_lshr_b32 s83, s83, 18
	s_mul_i32 s84, s83, 0x3400
	s_sub_i32 s84, s82, s84
	s_movk_i32 s85, 0x1400
	s_movk_i32 s86, 4
	s_cmpk_lt_u32 s84, 0x1400
	s_cselect_b32 s85, 0x400, s85
	s_cselect_b32 s86, 2, s86
	s_cselect_b32 s87, 1, 0
	s_movk_i32 s88, 0x600
	s_cmpk_lt_u32 s84, 0x400
	s_cselect_b32 s85, 0, s85
	s_cselect_b32 s86, 0, s86
	s_cselect_b32 s88, 0x780, s88
	s_sub_i32 s85, s84, s85
	s_lshr_b32 s85, s85, 3
	s_add_i32 s88, s88, s85
	s_lshr_b32 s89, s85, 3
	s_lshl_b32 s89, s89, 4
	s_and_b32 s90, s85, 7
	s_add_i32 s89, s89, s90
	s_cmp_eq_u32 s87, 1
	s_cselect_b32 s88, s88, s89
	s_lshl_b32 s89, 1, s86
	s_add_i32 s89, s89, -1
	s_and_b32 s89, s88, s89
	s_lshr_b32 s90, s88, s86
	s_lshr_b32 s91, 0x800, s86
	s_add_i32 s91, s91, 8
	s_mul_i32 s89, s89, s91
	s_add_i32 s89, s89, s90
	s_lshl_b32 s90, s86, 2
	s_mul_i32 s91, s83, 24
	s_add_i32 s91, s91, s90
	s_mul_i32 s91, s91, 0x880
	s_add_i32 s91, s91, s89
	s_lshl_b32 s91, s91, 7
	s_lshl_b32 s89, s83, 11
	s_add_i32 s89, s89, s88
	s_mul_i32 s89, s89, 0x1800
	s_lshl_b32 s90, s90, 8
	s_add_i32 s89, s89, s90
	v_add_u32_e32 v79, s89, v75
	v_add_u32_e32 v104, s91, v76
	global_load_dwordx4 v[88:91], v79, s[18:19]
	global_load_dwordx4 v[92:95], v79, s[18:19] offset:16
	s_waitcnt vmcnt(2)
	v_cvt_pk_bf16_f32 v96, v80, v81
	v_cvt_pk_bf16_f32 v97, v82, v83
	v_cvt_pk_bf16_f32 v98, v84, v85
	v_cvt_pk_bf16_f32 v99, v86, v87
	global_store_dwordx4 v78, v[96:99], s[48:49]
	s_waitcnt vmcnt(1)
	v_cvt_pk_bf16_f32 v100, v88, v89
	v_cvt_pk_bf16_f32 v101, v90, v91
	v_cvt_pk_bf16_f32 v102, v92, v93
	v_cvt_pk_bf16_f32 v103, v94, v95
	global_store_dwordx4 v104, v[100:103], s[48:49]
	s_add_i32 s81, s81, 2
	s_cmp_lt_u32 s81, 26
	s_cbranch_scc1 .Lg1_loop
.LBB0_148:
	s_or_b64 exec, exec, s[0:1]
	s_add_u32 s50, s74, 0x29265c00
	s_movk_i32 s0, 0x1a00
	s_addc_u32 s51, s75, 0
	v_cmp_gt_i32_e32 vcc, s0, v68
	s_and_saveexec_b64 s[10:11], vcc
	s_cbranch_execz .LBB0_168
	v_and_b32_e32 v2, 56, v3
	v_mov_b32_e32 v71, 0
	s_movk_i32 s0, 0x84
	v_lshl_add_u32 v3, v2, 1, v124
	v_mul_u32_u24_e32 v4, 0x84, v1
	v_lshlrev_b32_e32 v70, 2, v66
	v_lshlrev_b32_e32 v5, 6, v67
	v_mad_u32_u24 v69, v66, s0, v124
	v_lshl_add_u64 v[72:73], s[20:21], 0, v[70:71]
	v_lshl_add_u32 v67, s2, 9, v5
	s_lshl_b32 s24, s76, 6
	s_mov_b64 s[12:13], 0
	s_mov_b32 s25, 0x4ec4ec4f
	s_movk_i32 s26, 0xff30
	s_movk_i32 s27, 0x4f
	s_mov_b32 s28, 0x0
	s_mov_b32 s29, 0x2ad5802b
	s_movk_i32 s30, 0x5fa
	s_mov_b64 s[14:15], 0xc000
	s_movk_i32 s31, 0x800
	s_mov_b32 s34, 0x44000
	v_lshlrev_b32_e32 v74, 1, v2
	v_add_u32_e32 v111, v3, v4
	s_movk_i32 s35, 0x19ff
	v_mov_b32_e32 v112, 0x780
	v_mov_b32_e32 v113, 0x1f210000
	v_mov_b32_e32 v114, 0x7210000
	s_branch .LBB0_151

.LBB0_168:
	s_or_b64 exec, exec, s[10:11]
	s_mov_b32 s0, 0x0
	v_cmp_gt_i32_e32 vcc, s0, v110
	s_and_saveexec_b64 s[4:5], vcc
	s_cbranch_execz .LBB0_171
	v_mov_b32_e32 v3, 0
	v_lshlrev_b32_e32 v1, 9, v110
	s_lshl_b32 s14, s76, 9
	s_mov_b64 s[10:11], 0
	s_mov_b32 s15, 0x2ad5802b
	v_mov_b32_e32 v6, s21
	v_mov_b32_e32 v7, s19
	v_mov_b32_e32 v8, s20
	v_mov_b32_e32 v9, s18
	v_lshlrev_b32_e32 v4, 4, v66
	v_mov_b32_e32 v5, v3
	s_mov_b64 s[12:13], 0xc000
	s_mov_b32 s22, 0xd000
	s_waitcnt vmcnt(4)
	v_mov_b32_e32 v10, 0x1f210000
	v_mov_b32_e32 v11, 0x7210000
	s_mov_b32 s23, -0x1

.LBB0_243:
	ds_read_b128 v[144:147], v151
	ds_read_b128 v[156:159], v151 offset:1024
	ds_read_b128 v[160:163], v151 offset:2048
	ds_read_b128 v[164:167], v151 offset:3072
	s_add_u32 s30, s28, 0x100
	s_addc_u32 s31, s29, 0
	s_cmp_eq_u32 s82, 40
	s_cselect_b32 s37, s11, s31
	s_cselect_b32 s36, s10, s30
	s_cselect_b32 s35, s13, s81
	s_cselect_b32 s34, s12, s80
	v_lshl_add_u64 v[172:173], s[28:29], 0, v[136:137]
	s_add_i32 m0, s52, 0xc000
	ds_read_b128 v[168:171], v152
	ds_read_b128 v[176:179], v152 offset:1024
	ds_read_b128 v[180:183], v152 offset:2048
	ds_read_b128 v[184:187], v152 offset:3072
	ds_read_b128 v[188:191], v152 offset:4096
	ds_read_b128 v[192:195], v152 offset:5120
	ds_read_b128 v[196:199], v152 offset:6144
	ds_read_b128 v[200:203], v152 offset:7168
	global_load_lds_dwordx4 v[172:173], off
	v_lshl_add_u64 v[172:173], s[28:29], 0, v[138:139]
	s_add_i32 m0, s52, 0xe000
	s_nop 0
	global_load_lds_dwordx4 v[172:173], off
	s_waitcnt lgkmcnt(8)
	s_barrier
	s_waitcnt lgkmcnt(0)
	s_setprio 1
	s_waitcnt lgkmcnt(0)
	v_mfma_f32_16x16x32_bf16 v[124:127], v[144:147], v[168:171], v[124:127]
	v_mfma_f32_16x16x32_bf16 v[120:123], v[160:163], v[168:171], v[120:123]
	v_mfma_f32_16x16x32_bf16 v[108:111], v[144:147], v[180:183], v[108:111]
	v_mfma_f32_16x16x32_bf16 v[104:107], v[160:163], v[180:183], v[104:107]
	v_mfma_f32_16x16x32_bf16 v[92:95], v[144:147], v[188:191], v[92:95]
	v_mfma_f32_16x16x32_bf16 v[88:91], v[160:163], v[188:191], v[88:91]
	v_mfma_f32_16x16x32_bf16 v[76:79], v[144:147], v[196:199], v[76:79]
	v_mfma_f32_16x16x32_bf16 v[72:75], v[160:163], v[196:199], v[72:75]
	v_mfma_f32_16x16x32_bf16 v[124:127], v[156:159], v[176:179], v[124:127]
	v_mfma_f32_16x16x32_bf16 v[120:123], v[164:167], v[176:179], v[120:123]
	v_mfma_f32_16x16x32_bf16 v[108:111], v[156:159], v[184:187], v[108:111]
	v_mfma_f32_16x16x32_bf16 v[104:107], v[164:167], v[184:187], v[104:107]
	v_mfma_f32_16x16x32_bf16 v[92:95], v[156:159], v[192:195], v[92:95]
	v_mfma_f32_16x16x32_bf16 v[88:91], v[164:167], v[192:195], v[88:91]
	v_mfma_f32_16x16x32_bf16 v[76:79], v[156:159], v[200:203], v[76:79]
	v_mfma_f32_16x16x32_bf16 v[72:75], v[164:167], v[200:203], v[72:75]
	s_setprio 0
	s_barrier
	s_add_i32 s28, s65, s47
	v_lshl_add_u64 v[172:173], s[34:35], 0, v[130:131]
	s_mov_b32 m0, s28
	ds_read_b128 v[204:207], v153
	ds_read_b128 v[208:211], v153 offset:1024
	ds_read_b128 v[212:215], v153 offset:2048
	ds_read_b128 v[216:219], v153 offset:3072
	global_load_lds_dwordx4 v[172:173], off
	v_lshl_add_u64 v[220:221], s[34:35], 0, v[134:135]
	s_add_i32 m0, s28, 0x2000
	s_nop 0
	global_load_lds_dwordx4 v[220:221], off
	s_barrier
	s_waitcnt lgkmcnt(0)
	s_setprio 1
	s_waitcnt lgkmcnt(0)
	v_mfma_f32_16x16x32_bf16 v[116:119], v[204:207], v[168:171], v[116:119]
	v_mfma_f32_16x16x32_bf16 v[112:115], v[212:215], v[168:171], v[112:115]
	v_mfma_f32_16x16x32_bf16 v[100:103], v[204:207], v[180:183], v[100:103]
	v_mfma_f32_16x16x32_bf16 v[96:99], v[212:215], v[180:183], v[96:99]
	v_mfma_f32_16x16x32_bf16 v[84:87], v[204:207], v[188:191], v[84:87]
	v_mfma_f32_16x16x32_bf16 v[80:83], v[212:215], v[188:191], v[80:83]
	v_mfma_f32_16x16x32_bf16 v[68:71], v[204:207], v[196:199], v[68:71]
	v_mfma_f32_16x16x32_bf16 v[64:67], v[212:215], v[196:199], v[64:67]
	v_mfma_f32_16x16x32_bf16 v[116:119], v[208:211], v[176:179], v[116:119]
	v_mfma_f32_16x16x32_bf16 v[112:115], v[216:219], v[176:179], v[112:115]
	v_mfma_f32_16x16x32_bf16 v[100:103], v[208:211], v[184:187], v[100:103]
	v_mfma_f32_16x16x32_bf16 v[96:99], v[216:219], v[184:187], v[96:99]
	v_mfma_f32_16x16x32_bf16 v[84:87], v[208:211], v[192:195], v[84:87]
	v_mfma_f32_16x16x32_bf16 v[80:83], v[216:219], v[192:195], v[80:83]
	v_mfma_f32_16x16x32_bf16 v[68:71], v[208:211], v[200:203], v[68:71]
	v_mfma_f32_16x16x32_bf16 v[64:67], v[216:219], v[200:203], v[64:67]
	s_setprio 0
	s_mov_b32 m0, s52
	v_lshl_add_u64 v[222:223], s[36:37], 0, v[128:129]
	s_barrier
	ds_read_b128 v[168:171], v152 offset:16384
	ds_read_b128 v[176:179], v152 offset:17408
	ds_read_b128 v[180:183], v152 offset:18432
	ds_read_b128 v[184:187], v152 offset:19456
	ds_read_b128 v[188:191], v152 offset:20480
	ds_read_b128 v[192:195], v152 offset:21504
	ds_read_b128 v[196:199], v152 offset:22528
	ds_read_b128 v[200:203], v152 offset:23552
	global_load_lds_dwordx4 v[222:223], off
	v_lshl_add_u64 v[224:225], s[36:37], 0, v[132:133]
	s_mov_b32 m0, s53
	s_nop 0
	global_load_lds_dwordx4 v[224:225], off
	s_barrier
	s_waitcnt lgkmcnt(0)
	s_setprio 1
	s_waitcnt lgkmcnt(0)
	v_mfma_f32_16x16x32_bf16 v[60:63], v[144:147], v[168:171], v[60:63]
	v_mfma_f32_16x16x32_bf16 v[56:59], v[160:163], v[168:171], v[56:59]
	v_mfma_f32_16x16x32_bf16 v[44:47], v[144:147], v[180:183], v[44:47]
	v_mfma_f32_16x16x32_bf16 v[40:43], v[160:163], v[180:183], v[40:43]
	v_mfma_f32_16x16x32_bf16 v[28:31], v[144:147], v[188:191], v[28:31]
	v_mfma_f32_16x16x32_bf16 v[24:27], v[160:163], v[188:191], v[24:27]
	v_mfma_f32_16x16x32_bf16 v[12:15], v[144:147], v[196:199], v[12:15]
	v_mfma_f32_16x16x32_bf16 v[8:11], v[160:163], v[196:199], v[8:11]
	v_mfma_f32_16x16x32_bf16 v[60:63], v[156:159], v[176:179], v[60:63]
	v_mfma_f32_16x16x32_bf16 v[56:59], v[164:167], v[176:179], v[56:59]
	v_mfma_f32_16x16x32_bf16 v[44:47], v[156:159], v[184:187], v[44:47]
	v_mfma_f32_16x16x32_bf16 v[40:43], v[164:167], v[184:187], v[40:43]
	v_mfma_f32_16x16x32_bf16 v[28:31], v[156:159], v[192:195], v[28:31]
	v_mfma_f32_16x16x32_bf16 v[24:27], v[164:167], v[192:195], v[24:27]
	v_mfma_f32_16x16x32_bf16 v[12:15], v[156:159], v[200:203], v[12:15]
	v_mfma_f32_16x16x32_bf16 v[8:11], v[164:167], v[200:203], v[8:11]
	s_setprio 0
	s_barrier
	s_add_u32 s28, s34, 0xb0000
	s_addc_u32 s29, s35, 0
	s_add_i32 s83, s66, s47
	v_lshl_add_u64 v[144:145], s[28:29], 0, v[130:131]
	s_mov_b32 m0, s83
	s_nop 0
	global_load_lds_dwordx4 v[144:145], off
	v_lshl_add_u64 v[144:145], s[28:29], 0, v[134:135]
	s_add_i32 m0, s83, 0x2000
	s_nop 0
	global_load_lds_dwordx4 v[144:145], off
	s_waitcnt vmcnt(6)
	s_barrier
	s_setprio 1
	v_mfma_f32_16x16x32_bf16 v[52:55], v[204:207], v[168:171], v[52:55]
	v_mfma_f32_16x16x32_bf16 v[48:51], v[212:215], v[168:171], v[48:51]
	v_mfma_f32_16x16x32_bf16 v[36:39], v[204:207], v[180:183], v[36:39]
	v_mfma_f32_16x16x32_bf16 v[32:35], v[212:215], v[180:183], v[32:35]
	v_mfma_f32_16x16x32_bf16 v[20:23], v[204:207], v[188:191], v[20:23]
	v_mfma_f32_16x16x32_bf16 v[16:19], v[212:215], v[188:191], v[16:19]
	v_mfma_f32_16x16x32_bf16 v[4:7], v[204:207], v[196:199], v[4:7]
	v_mfma_f32_16x16x32_bf16 v[0:3], v[212:215], v[196:199], v[0:3]
	v_mfma_f32_16x16x32_bf16 v[52:55], v[208:211], v[176:179], v[52:55]
	v_mfma_f32_16x16x32_bf16 v[48:51], v[216:219], v[176:179], v[48:51]
	v_mfma_f32_16x16x32_bf16 v[36:39], v[208:211], v[184:187], v[36:39]
	v_mfma_f32_16x16x32_bf16 v[32:35], v[216:219], v[184:187], v[32:35]
	v_mfma_f32_16x16x32_bf16 v[20:23], v[208:211], v[192:195], v[20:23]
	v_mfma_f32_16x16x32_bf16 v[16:19], v[216:219], v[192:195], v[16:19]
	v_mfma_f32_16x16x32_bf16 v[4:7], v[208:211], v[200:203], v[4:7]
	v_mfma_f32_16x16x32_bf16 v[0:3], v[216:219], v[200:203], v[0:3]
	s_setprio 0
	s_add_i32 s83, 0, 0x18000
	v_add_u32_e32 v155, s83, v149
	s_barrier
	ds_read_b128 v[144:147], v155
	ds_read_b128 v[156:159], v155 offset:1024
	ds_read_b128 v[160:163], v155 offset:2048
	ds_read_b128 v[164:167], v155 offset:3072
	s_add_u32 s28, s36, 0xb0000
	s_addc_u32 s29, s37, 0
	s_mov_b32 m0, s54
	v_lshl_add_u64 v[204:205], s[28:29], 0, v[128:129]
	ds_read_b128 v[168:171], v152 offset:32768
	ds_read_b128 v[176:179], v152 offset:33792
	ds_read_b128 v[180:183], v152 offset:34816
	ds_read_b128 v[184:187], v152 offset:35840
	ds_read_b128 v[188:191], v152 offset:36864
	ds_read_b128 v[192:195], v152 offset:37888
	ds_read_b128 v[196:199], v152 offset:38912
	ds_read_b128 v[200:203], v152 offset:39936
	global_load_lds_dwordx4 v[204:205], off
	v_lshl_add_u64 v[204:205], s[28:29], 0, v[132:133]
	s_mov_b32 m0, s55
	s_nop 0
	global_load_lds_dwordx4 v[204:205], off
	s_waitcnt lgkmcnt(8)
	s_barrier
	s_waitcnt lgkmcnt(0)
	s_setprio 1
	s_waitcnt lgkmcnt(0)
	v_mfma_f32_16x16x32_bf16 v[124:127], v[144:147], v[168:171], v[124:127]
	v_mfma_f32_16x16x32_bf16 v[120:123], v[160:163], v[168:171], v[120:123]
	v_mfma_f32_16x16x32_bf16 v[108:111], v[144:147], v[180:183], v[108:111]
	v_mfma_f32_16x16x32_bf16 v[104:107], v[160:163], v[180:183], v[104:107]
	v_mfma_f32_16x16x32_bf16 v[92:95], v[144:147], v[188:191], v[92:95]
	v_mfma_f32_16x16x32_bf16 v[88:91], v[160:163], v[188:191], v[88:91]
	v_mfma_f32_16x16x32_bf16 v[76:79], v[144:147], v[196:199], v[76:79]
	v_mfma_f32_16x16x32_bf16 v[72:75], v[160:163], v[196:199], v[72:75]
	v_mfma_f32_16x16x32_bf16 v[124:127], v[156:159], v[176:179], v[124:127]
	v_mfma_f32_16x16x32_bf16 v[120:123], v[164:167], v[176:179], v[120:123]
	v_mfma_f32_16x16x32_bf16 v[108:111], v[156:159], v[184:187], v[108:111]
	v_mfma_f32_16x16x32_bf16 v[104:107], v[164:167], v[184:187], v[104:107]
	v_mfma_f32_16x16x32_bf16 v[92:95], v[156:159], v[192:195], v[92:95]
	v_mfma_f32_16x16x32_bf16 v[88:91], v[164:167], v[192:195], v[88:91]
	v_mfma_f32_16x16x32_bf16 v[76:79], v[156:159], v[200:203], v[76:79]
	v_mfma_f32_16x16x32_bf16 v[72:75], v[164:167], v[200:203], v[72:75]
	s_setprio 0
	s_barrier
	s_add_i32 s36, 0, 0x1c000
	s_add_i32 s28, s83, s47
	v_add_u32_e32 v155, s36, v149
	v_lshl_add_u64 v[172:173], v[172:173], 0, s[24:25]
	s_mov_b32 m0, s28
	ds_read_b128 v[204:207], v155
	ds_read_b128 v[208:211], v155 offset:1024
	ds_read_b128 v[212:215], v155 offset:2048
	ds_read_b128 v[216:219], v155 offset:3072
	global_load_lds_dwordx4 v[172:173], off
	v_lshl_add_u64 v[172:173], v[220:221], 0, s[24:25]
	s_add_i32 m0, s28, 0x2000
	s_nop 0
	global_load_lds_dwordx4 v[172:173], off
	s_barrier
	s_waitcnt lgkmcnt(0)
	s_setprio 1
	s_waitcnt lgkmcnt(0)
	v_mfma_f32_16x16x32_bf16 v[116:119], v[204:207], v[168:171], v[116:119]
	v_mfma_f32_16x16x32_bf16 v[112:115], v[212:215], v[168:171], v[112:115]
	v_mfma_f32_16x16x32_bf16 v[100:103], v[204:207], v[180:183], v[100:103]
	v_mfma_f32_16x16x32_bf16 v[96:99], v[212:215], v[180:183], v[96:99]
	v_mfma_f32_16x16x32_bf16 v[84:87], v[204:207], v[188:191], v[84:87]
	v_mfma_f32_16x16x32_bf16 v[80:83], v[212:215], v[188:191], v[80:83]
	v_mfma_f32_16x16x32_bf16 v[68:71], v[204:207], v[196:199], v[68:71]
	v_mfma_f32_16x16x32_bf16 v[64:67], v[212:215], v[196:199], v[64:67]
	v_mfma_f32_16x16x32_bf16 v[116:119], v[208:211], v[176:179], v[116:119]
	v_mfma_f32_16x16x32_bf16 v[112:115], v[216:219], v[176:179], v[112:115]
	v_mfma_f32_16x16x32_bf16 v[100:103], v[208:211], v[184:187], v[100:103]
	v_mfma_f32_16x16x32_bf16 v[96:99], v[216:219], v[184:187], v[96:99]
	v_mfma_f32_16x16x32_bf16 v[84:87], v[208:211], v[192:195], v[84:87]
	v_mfma_f32_16x16x32_bf16 v[80:83], v[216:219], v[192:195], v[80:83]
	v_mfma_f32_16x16x32_bf16 v[68:71], v[208:211], v[200:203], v[68:71]
	v_mfma_f32_16x16x32_bf16 v[64:67], v[216:219], v[200:203], v[64:67]
	s_setprio 0
	s_mov_b32 m0, s57
	v_lshl_add_u64 v[172:173], v[222:223], 0, s[24:25]
	s_barrier
	ds_read_b128 v[168:171], v152 offset:49152
	ds_read_b128 v[176:179], v152 offset:50176
	ds_read_b128 v[180:183], v152 offset:51200
	ds_read_b128 v[184:187], v152 offset:52224
	ds_read_b128 v[188:191], v152 offset:53248
	ds_read_b128 v[192:195], v152 offset:54272
	ds_read_b128 v[196:199], v152 offset:55296
	ds_read_b128 v[200:203], v152 offset:56320
	global_load_lds_dwordx4 v[172:173], off
	v_lshl_add_u64 v[172:173], v[224:225], 0, s[24:25]
	s_mov_b32 m0, s62
	s_nop 0
	global_load_lds_dwordx4 v[172:173], off
	s_barrier
	s_waitcnt lgkmcnt(0)
	s_setprio 1
	s_waitcnt lgkmcnt(0)
	v_mfma_f32_16x16x32_bf16 v[60:63], v[144:147], v[168:171], v[60:63]
	v_mfma_f32_16x16x32_bf16 v[56:59], v[160:163], v[168:171], v[56:59]
	v_mfma_f32_16x16x32_bf16 v[44:47], v[144:147], v[180:183], v[44:47]
	v_mfma_f32_16x16x32_bf16 v[40:43], v[160:163], v[180:183], v[40:43]
	v_mfma_f32_16x16x32_bf16 v[28:31], v[144:147], v[188:191], v[28:31]
	v_mfma_f32_16x16x32_bf16 v[24:27], v[160:163], v[188:191], v[24:27]
	v_mfma_f32_16x16x32_bf16 v[12:15], v[144:147], v[196:199], v[12:15]
	v_mfma_f32_16x16x32_bf16 v[8:11], v[160:163], v[196:199], v[8:11]
	v_mfma_f32_16x16x32_bf16 v[60:63], v[156:159], v[176:179], v[60:63]
	v_mfma_f32_16x16x32_bf16 v[56:59], v[164:167], v[176:179], v[56:59]
	v_mfma_f32_16x16x32_bf16 v[44:47], v[156:159], v[184:187], v[44:47]
	v_mfma_f32_16x16x32_bf16 v[40:43], v[164:167], v[184:187], v[40:43]
	v_mfma_f32_16x16x32_bf16 v[28:31], v[156:159], v[192:195], v[28:31]
	v_mfma_f32_16x16x32_bf16 v[24:27], v[164:167], v[192:195], v[24:27]
	v_mfma_f32_16x16x32_bf16 v[12:15], v[156:159], v[200:203], v[12:15]
	v_mfma_f32_16x16x32_bf16 v[8:11], v[164:167], v[200:203], v[8:11]
	s_setprio 0
	s_barrier
	s_add_u32 s28, s34, 0xb0080
	s_addc_u32 s29, s35, 0
	s_add_i32 s34, s36, s47
	v_lshl_add_u64 v[144:145], s[28:29], 0, v[130:131]
	s_mov_b32 m0, s34
	s_nop 0
	global_load_lds_dwordx4 v[144:145], off
	v_lshl_add_u64 v[144:145], s[28:29], 0, v[134:135]
	s_add_i32 m0, s34, 0x2000
	s_nop 0
	global_load_lds_dwordx4 v[144:145], off
	s_waitcnt vmcnt(6)
	s_barrier
	s_setprio 1
	v_mfma_f32_16x16x32_bf16 v[52:55], v[204:207], v[168:171], v[52:55]
	v_mfma_f32_16x16x32_bf16 v[48:51], v[212:215], v[168:171], v[48:51]
	v_mfma_f32_16x16x32_bf16 v[36:39], v[204:207], v[180:183], v[36:39]
	v_mfma_f32_16x16x32_bf16 v[32:35], v[212:215], v[180:183], v[32:35]
	v_mfma_f32_16x16x32_bf16 v[20:23], v[204:207], v[188:191], v[20:23]
	v_mfma_f32_16x16x32_bf16 v[16:19], v[212:215], v[188:191], v[16:19]
	v_mfma_f32_16x16x32_bf16 v[4:7], v[204:207], v[196:199], v[4:7]
	v_mfma_f32_16x16x32_bf16 v[0:3], v[212:215], v[196:199], v[0:3]
	v_mfma_f32_16x16x32_bf16 v[52:55], v[208:211], v[176:179], v[52:55]
	v_mfma_f32_16x16x32_bf16 v[48:51], v[216:219], v[176:179], v[48:51]
	v_mfma_f32_16x16x32_bf16 v[36:39], v[208:211], v[184:187], v[36:39]
	v_mfma_f32_16x16x32_bf16 v[32:35], v[216:219], v[184:187], v[32:35]
	v_mfma_f32_16x16x32_bf16 v[20:23], v[208:211], v[192:195], v[20:23]
	v_mfma_f32_16x16x32_bf16 v[16:19], v[216:219], v[192:195], v[16:19]
	v_mfma_f32_16x16x32_bf16 v[4:7], v[208:211], v[200:203], v[4:7]
	v_mfma_f32_16x16x32_bf16 v[0:3], v[216:219], v[200:203], v[0:3]
	s_setprio 0
	s_add_i32 s82, s82, 2
	s_add_u32 s80, s80, 0x100
	s_addc_u32 s81, s81, 0
	s_cmp_gt_u32 s82, 41
	s_mov_b64 s[28:29], s[30:31]
	s_barrier
	s_cbranch_scc0 .LBB0_243
	v_lshl_add_u32 v146, s77, 8, v148
	v_ashrrev_i32_e32 v147, 31, v146
	v_lshl_or_b32 v144, s69, 8, v150
	v_lshlrev_b64 v[156:157], 12, v[146:147]
	v_lshl_add_u64 v[156:157], s[38:39], 0, v[156:157]
	v_ashrrev_i32_e32 v145, 31, v144
	v_lshl_add_u64 v[168:169], v[144:145], 2, v[156:157]
	global_load_dwordx4 v[156:159], v[168:169], off
	global_load_dwordx4 v[160:163], v[168:169], off offset:16
	v_lshlrev_b64 v[164:165], 11, v[146:147]
	v_lshl_add_u64 v[164:165], s[40:41], 0, v[164:165]
	v_lshl_add_u64 v[170:171], v[144:145], 1, v[164:165]
	v_xor_b32_e32 v155, 32, v154
	s_waitcnt vmcnt(0)
	v_pk_fma_f32 v[126:127], v[126:127], 0.5, v[158:159] op_sel_hi:[1,0,1]
	v_pk_fma_f32 v[124:125], v[124:125], 0.5, v[156:157] op_sel_hi:[1,0,1]
	v_pk_fma_f32 v[158:159], v[122:123], 0.5, v[162:163] op_sel_hi:[1,0,1]
	v_pk_fma_f32 v[156:157], v[120:121], 0.5, v[160:161] op_sel_hi:[1,0,1]
	global_store_dwordx4 v[168:169], v[124:127], off
	global_store_dwordx4 v[168:169], v[156:159], off offset:16
	v_cvt_pk_bf16_f32 v120, v124, v125
	v_cvt_pk_bf16_f32 v121, v126, v127
	v_cvt_pk_bf16_f32 v122, v156, v157
	v_cvt_pk_bf16_f32 v123, v158, v159
	global_load_dwordx4 v[160:163], v[168:169], off offset:512
	global_load_dwordx4 v[164:167], v[168:169], off offset:528
	v_mul_f32_e32 v122, v125, v125
	v_mul_f32_e32 v123, v127, v127
	v_mul_f32_e32 v125, v157, v157
	v_fmac_f32_e32 v122, v124, v124
	v_fmac_f32_e32 v123, v126, v126
	v_mul_f32_e32 v127, v159, v159
	v_fmac_f32_e32 v125, v156, v156
	v_add_f32_e32 v122, v122, v123
	v_fmac_f32_e32 v127, v158, v158
	v_add_f32_e32 v122, v125, v122
	v_add_f32_e32 v126, v127, v122
	v_and_b32_e32 v121, 64, v154
	v_xor_b32_e32 v120, 16, v154
	v_add_u32_e32 v121, 64, v121
	v_cmp_lt_i32_e32 vcc, v120, v121
	s_waitcnt vmcnt(0)
	v_pk_fma_f32 v[118:119], v[118:119], 0.5, v[162:163] op_sel_hi:[1,0,1]
	v_pk_fma_f32 v[116:117], v[116:117], 0.5, v[160:161] op_sel_hi:[1,0,1]
	v_pk_fma_f32 v[122:123], v[112:113], 0.5, v[164:165] op_sel_hi:[1,0,1]
	v_mul_f32_e32 v112, v117, v117
	v_mul_f32_e32 v113, v119, v119
	v_pk_fma_f32 v[124:125], v[114:115], 0.5, v[166:167] op_sel_hi:[1,0,1]
	v_mul_f32_e32 v114, v123, v123
	v_fmac_f32_e32 v112, v116, v116
	v_fmac_f32_e32 v113, v118, v118
	v_mul_f32_e32 v115, v125, v125
	v_fmac_f32_e32 v114, v122, v122
	v_add_f32_e32 v112, v112, v113
	v_fmac_f32_e32 v115, v124, v124
	v_add_f32_e32 v112, v114, v112
	v_cndmask_b32_e32 v120, v154, v120, vcc
	v_add_f32_e32 v112, v115, v112
	v_lshlrev_b32_e32 v120, 2, v120
	v_add_f32_e32 v112, v126, v112
	ds_bpermute_b32 v113, v120, v112
	v_cmp_lt_i32_e32 vcc, v155, v121
	global_store_dwordx4 v[168:169], v[116:119], off offset:512
	global_store_dwordx4 v[168:169], v[122:125], off offset:528
	v_cndmask_b32_e32 v114, v154, v155, vcc
	v_lshlrev_b32_e32 v114, 2, v114
	s_waitcnt lgkmcnt(0)
	v_add_f32_e32 v112, v112, v113
	ds_bpermute_b32 v113, v114, v112
	v_cvt_pk_bf16_f32 v116, v116, v117
	v_cvt_pk_bf16_f32 v117, v118, v119
	v_cvt_pk_bf16_f32 v118, v122, v123
	v_cvt_pk_bf16_f32 v119, v124, v125
	s_and_saveexec_b64 s[28:29], s[6:7]
	s_cbranch_execz .LBB0_246
	v_lshl_add_u64 v[116:117], v[146:147], 2, s[22:23]
	s_waitcnt lgkmcnt(0)
	v_add_f32_e32 v112, v112, v113
	global_atomic_add_f32 v[116:117], v112, off
.LBB0_246:
	s_or_b64 exec, exec, s[28:29]
	v_or_b32_e32 v112, 16, v146
	s_waitcnt lgkmcnt(0)
	v_ashrrev_i32_e32 v113, 31, v112
	v_lshlrev_b64 v[116:117], 12, v[112:113]
	v_lshl_add_u64 v[116:117], s[38:39], 0, v[116:117]
	v_lshl_add_u64 v[126:127], v[144:145], 2, v[116:117]
	global_load_dwordx4 v[116:119], v[126:127], off
	global_load_dwordx4 v[122:125], v[126:127], off offset:16
	v_lshlrev_b64 v[156:157], 11, v[112:113]
	v_lshl_add_u64 v[156:157], s[40:41], 0, v[156:157]
	v_lshl_add_u64 v[156:157], v[144:145], 1, v[156:157]
	s_waitcnt vmcnt(1)
	v_pk_fma_f32 v[110:111], v[110:111], 0.5, v[118:119] op_sel_hi:[1,0,1]
	v_pk_fma_f32 v[108:109], v[108:109], 0.5, v[116:117] op_sel_hi:[1,0,1]
	s_waitcnt vmcnt(0)
	v_pk_fma_f32 v[106:107], v[106:107], 0.5, v[124:125] op_sel_hi:[1,0,1]
	v_pk_fma_f32 v[104:105], v[104:105], 0.5, v[122:123] op_sel_hi:[1,0,1]
	global_store_dwordx4 v[126:127], v[108:111], off
	global_store_dwordx4 v[126:127], v[104:107], off offset:16
	v_cvt_pk_bf16_f32 v116, v108, v109
	v_cvt_pk_bf16_f32 v117, v110, v111
	v_cvt_pk_bf16_f32 v118, v104, v105
	v_cvt_pk_bf16_f32 v119, v106, v107
	global_load_dwordx4 v[116:119], v[126:127], off offset:512
	s_nop 0
	global_load_dwordx4 v[122:125], v[126:127], off offset:528
	v_mul_f32_e32 v109, v109, v109
	v_mul_f32_e32 v111, v111, v111
	v_mul_f32_e32 v105, v105, v105
	v_fmac_f32_e32 v109, v108, v108
	v_fmac_f32_e32 v111, v110, v110
	v_mul_f32_e32 v107, v107, v107
	v_fmac_f32_e32 v105, v104, v104
	v_add_f32_e32 v104, v109, v111
	v_fmac_f32_e32 v107, v106, v106
	v_add_f32_e32 v104, v105, v104
	v_add_f32_e32 v108, v107, v104
	s_waitcnt vmcnt(1)
	v_pk_fma_f32 v[102:103], v[102:103], 0.5, v[118:119] op_sel_hi:[1,0,1]
	v_pk_fma_f32 v[100:101], v[100:101], 0.5, v[116:117] op_sel_hi:[1,0,1]
	s_waitcnt vmcnt(0)
	v_pk_fma_f32 v[104:105], v[96:97], 0.5, v[122:123] op_sel_hi:[1,0,1]
	v_mul_f32_e32 v96, v101, v101
	v_mul_f32_e32 v97, v103, v103
	v_pk_fma_f32 v[106:107], v[98:99], 0.5, v[124:125] op_sel_hi:[1,0,1]
	v_mul_f32_e32 v98, v105, v105
	v_fmac_f32_e32 v96, v100, v100
	v_fmac_f32_e32 v97, v102, v102
	v_mul_f32_e32 v99, v107, v107
	v_fmac_f32_e32 v98, v104, v104
	v_add_f32_e32 v96, v96, v97
	v_add_f32_e32 v96, v98, v96
	v_fmac_f32_e32 v99, v106, v106
	v_add_f32_e32 v96, v99, v96
	v_add_f32_e32 v96, v108, v96
	ds_bpermute_b32 v97, v120, v96
	global_store_dwordx4 v[126:127], v[100:103], off offset:512
	global_store_dwordx4 v[126:127], v[104:107], off offset:528
	v_cvt_pk_bf16_f32 v98, v100, v101
	v_cvt_pk_bf16_f32 v99, v102, v103
	s_waitcnt lgkmcnt(0)
	v_add_f32_e32 v96, v96, v97
	ds_bpermute_b32 v97, v114, v96
	v_cvt_pk_bf16_f32 v100, v104, v105
	v_cvt_pk_bf16_f32 v101, v106, v107
	s_and_saveexec_b64 s[28:29], s[6:7]
	s_cbranch_execz .LBB0_248
	v_lshl_add_u64 v[98:99], v[112:113], 2, s[22:23]
	s_waitcnt lgkmcnt(0)
	v_add_f32_e32 v96, v96, v97
	global_atomic_add_f32 v[98:99], v96, off
.LBB0_248:
	s_or_b64 exec, exec, s[28:29]
	v_or_b32_e32 v96, 32, v146
	s_waitcnt lgkmcnt(0)
	v_ashrrev_i32_e32 v97, 31, v96
	v_lshlrev_b64 v[98:99], 12, v[96:97]
	v_lshl_add_u64 v[98:99], s[38:39], 0, v[98:99]
	v_lshl_add_u64 v[106:107], v[144:145], 2, v[98:99]
	global_load_dwordx4 v[98:101], v[106:107], off
	global_load_dwordx4 v[102:105], v[106:107], off offset:16
	v_lshlrev_b64 v[108:109], 11, v[96:97]
	v_lshl_add_u64 v[108:109], s[40:41], 0, v[108:109]
	v_lshl_add_u64 v[108:109], v[144:145], 1, v[108:109]
	s_waitcnt vmcnt(1)
	v_pk_fma_f32 v[94:95], v[94:95], 0.5, v[100:101] op_sel_hi:[1,0,1]
	v_pk_fma_f32 v[92:93], v[92:93], 0.5, v[98:99] op_sel_hi:[1,0,1]
	s_waitcnt vmcnt(0)
	v_pk_fma_f32 v[90:91], v[90:91], 0.5, v[104:105] op_sel_hi:[1,0,1]
	v_pk_fma_f32 v[88:89], v[88:89], 0.5, v[102:103] op_sel_hi:[1,0,1]
	global_store_dwordx4 v[106:107], v[92:95], off
	global_store_dwordx4 v[106:107], v[88:91], off offset:16
	v_cvt_pk_bf16_f32 v98, v92, v93
	v_cvt_pk_bf16_f32 v99, v94, v95
	v_cvt_pk_bf16_f32 v100, v88, v89
	v_cvt_pk_bf16_f32 v101, v90, v91
	global_load_dwordx4 v[98:101], v[106:107], off offset:512
	s_nop 0
	global_load_dwordx4 v[102:105], v[106:107], off offset:528
	v_mul_f32_e32 v93, v93, v93
	v_mul_f32_e32 v95, v95, v95
	v_mul_f32_e32 v89, v89, v89
	v_fmac_f32_e32 v93, v92, v92
	v_fmac_f32_e32 v95, v94, v94
	v_mul_f32_e32 v91, v91, v91
	v_fmac_f32_e32 v89, v88, v88
	v_add_f32_e32 v88, v93, v95
	v_fmac_f32_e32 v91, v90, v90
	v_add_f32_e32 v88, v89, v88
	v_add_f32_e32 v92, v91, v88
	s_waitcnt vmcnt(1)
	v_pk_fma_f32 v[86:87], v[86:87], 0.5, v[100:101] op_sel_hi:[1,0,1]
	v_pk_fma_f32 v[84:85], v[84:85], 0.5, v[98:99] op_sel_hi:[1,0,1]
	s_waitcnt vmcnt(0)
	v_pk_fma_f32 v[88:89], v[80:81], 0.5, v[102:103] op_sel_hi:[1,0,1]
	v_mul_f32_e32 v80, v85, v85
	v_mul_f32_e32 v81, v87, v87
	v_pk_fma_f32 v[90:91], v[82:83], 0.5, v[104:105] op_sel_hi:[1,0,1]
	v_mul_f32_e32 v82, v89, v89
	v_fmac_f32_e32 v80, v84, v84
	v_fmac_f32_e32 v81, v86, v86
	v_mul_f32_e32 v83, v91, v91
	v_fmac_f32_e32 v82, v88, v88
	v_add_f32_e32 v80, v80, v81
	v_add_f32_e32 v80, v82, v80
	v_fmac_f32_e32 v83, v90, v90
	v_add_f32_e32 v80, v83, v80
	v_add_f32_e32 v80, v92, v80
	ds_bpermute_b32 v81, v120, v80
	global_store_dwordx4 v[106:107], v[84:87], off offset:512
	global_store_dwordx4 v[106:107], v[88:91], off offset:528
	v_cvt_pk_bf16_f32 v82, v84, v85
	v_cvt_pk_bf16_f32 v83, v86, v87
	s_waitcnt lgkmcnt(0)
	v_add_f32_e32 v80, v80, v81
	ds_bpermute_b32 v81, v114, v80
	v_cvt_pk_bf16_f32 v84, v88, v89
	v_cvt_pk_bf16_f32 v85, v90, v91
	s_and_saveexec_b64 s[28:29], s[6:7]
	s_cbranch_execz .LBB0_250
	v_lshl_add_u64 v[82:83], v[96:97], 2, s[22:23]
	s_waitcnt lgkmcnt(0)
	v_add_f32_e32 v80, v80, v81
	global_atomic_add_f32 v[82:83], v80, off
.LBB0_250:
	s_or_b64 exec, exec, s[28:29]
	v_or_b32_e32 v80, 48, v146
	s_waitcnt lgkmcnt(0)
	v_ashrrev_i32_e32 v81, 31, v80
	v_lshlrev_b64 v[82:83], 12, v[80:81]
	v_lshl_add_u64 v[82:83], s[38:39], 0, v[82:83]
	v_lshl_add_u64 v[90:91], v[144:145], 2, v[82:83]
	global_load_dwordx4 v[82:85], v[90:91], off
	global_load_dwordx4 v[86:89], v[90:91], off offset:16
	v_lshlrev_b64 v[92:93], 11, v[80:81]
	v_lshl_add_u64 v[92:93], s[40:41], 0, v[92:93]
	v_lshl_add_u64 v[92:93], v[144:145], 1, v[92:93]
	s_waitcnt vmcnt(1)
	v_pk_fma_f32 v[78:79], v[78:79], 0.5, v[84:85] op_sel_hi:[1,0,1]
	v_pk_fma_f32 v[76:77], v[76:77], 0.5, v[82:83] op_sel_hi:[1,0,1]
	s_waitcnt vmcnt(0)
	v_pk_fma_f32 v[74:75], v[74:75], 0.5, v[88:89] op_sel_hi:[1,0,1]
	v_pk_fma_f32 v[72:73], v[72:73], 0.5, v[86:87] op_sel_hi:[1,0,1]
	global_store_dwordx4 v[90:91], v[76:79], off
	global_store_dwordx4 v[90:91], v[72:75], off offset:16
	v_cvt_pk_bf16_f32 v82, v76, v77
	v_cvt_pk_bf16_f32 v83, v78, v79
	v_cvt_pk_bf16_f32 v84, v72, v73
	v_cvt_pk_bf16_f32 v85, v74, v75
	global_load_dwordx4 v[82:85], v[90:91], off offset:512
	s_nop 0
	global_load_dwordx4 v[86:89], v[90:91], off offset:528
	v_mul_f32_e32 v77, v77, v77
	v_mul_f32_e32 v79, v79, v79
	v_mul_f32_e32 v73, v73, v73
	v_fmac_f32_e32 v77, v76, v76
	v_fmac_f32_e32 v79, v78, v78
	v_mul_f32_e32 v75, v75, v75
	v_fmac_f32_e32 v73, v72, v72
	v_add_f32_e32 v72, v77, v79
	v_fmac_f32_e32 v75, v74, v74
	v_add_f32_e32 v72, v73, v72
	v_add_f32_e32 v76, v75, v72
	s_waitcnt vmcnt(1)
	v_pk_fma_f32 v[70:71], v[70:71], 0.5, v[84:85] op_sel_hi:[1,0,1]
	v_pk_fma_f32 v[68:69], v[68:69], 0.5, v[82:83] op_sel_hi:[1,0,1]
	s_waitcnt vmcnt(0)
	v_pk_fma_f32 v[72:73], v[64:65], 0.5, v[86:87] op_sel_hi:[1,0,1]
	v_mul_f32_e32 v64, v69, v69
	v_mul_f32_e32 v65, v71, v71
	v_pk_fma_f32 v[74:75], v[66:67], 0.5, v[88:89] op_sel_hi:[1,0,1]
	v_mul_f32_e32 v66, v73, v73
	v_fmac_f32_e32 v64, v68, v68
	v_fmac_f32_e32 v65, v70, v70
	v_mul_f32_e32 v67, v75, v75
	v_fmac_f32_e32 v66, v72, v72
	v_add_f32_e32 v64, v64, v65
	v_add_f32_e32 v64, v66, v64
	v_fmac_f32_e32 v67, v74, v74
	v_add_f32_e32 v64, v67, v64
	v_add_f32_e32 v64, v76, v64
	ds_bpermute_b32 v65, v120, v64
	global_store_dwordx4 v[90:91], v[68:71], off offset:512
	global_store_dwordx4 v[90:91], v[72:75], off offset:528
	v_cvt_pk_bf16_f32 v66, v68, v69
	v_cvt_pk_bf16_f32 v67, v70, v71
	s_waitcnt lgkmcnt(0)
	v_add_f32_e32 v64, v64, v65
	ds_bpermute_b32 v65, v114, v64
	v_cvt_pk_bf16_f32 v68, v72, v73
	v_cvt_pk_bf16_f32 v69, v74, v75
	s_and_saveexec_b64 s[28:29], s[6:7]
	s_cbranch_execz .LBB0_252
	v_lshl_add_u64 v[66:67], v[80:81], 2, s[22:23]
	s_waitcnt lgkmcnt(0)
	v_add_f32_e32 v64, v64, v65
	global_atomic_add_f32 v[66:67], v64, off
.LBB0_252:
	s_or_b64 exec, exec, s[28:29]
	v_add_u32_e32 v64, 0x80, v146
	s_waitcnt lgkmcnt(0)
	v_ashrrev_i32_e32 v65, 31, v64
	v_lshlrev_b64 v[66:67], 12, v[64:65]
	v_lshl_add_u64 v[66:67], s[38:39], 0, v[66:67]
	v_lshl_add_u64 v[74:75], v[144:145], 2, v[66:67]
	global_load_dwordx4 v[66:69], v[74:75], off
	global_load_dwordx4 v[70:73], v[74:75], off offset:16
	v_lshlrev_b64 v[76:77], 11, v[64:65]
	v_lshl_add_u64 v[76:77], s[40:41], 0, v[76:77]
	v_lshl_add_u64 v[76:77], v[144:145], 1, v[76:77]
	s_waitcnt vmcnt(1)
	v_pk_fma_f32 v[62:63], v[62:63], 0.5, v[68:69] op_sel_hi:[1,0,1]
	v_pk_fma_f32 v[60:61], v[60:61], 0.5, v[66:67] op_sel_hi:[1,0,1]
	s_waitcnt vmcnt(0)
	v_pk_fma_f32 v[58:59], v[58:59], 0.5, v[72:73] op_sel_hi:[1,0,1]
	v_pk_fma_f32 v[56:57], v[56:57], 0.5, v[70:71] op_sel_hi:[1,0,1]
	global_store_dwordx4 v[74:75], v[60:63], off
	global_store_dwordx4 v[74:75], v[56:59], off offset:16
	v_cvt_pk_bf16_f32 v66, v60, v61
	v_cvt_pk_bf16_f32 v67, v62, v63
	v_cvt_pk_bf16_f32 v68, v56, v57
	v_cvt_pk_bf16_f32 v69, v58, v59
	global_load_dwordx4 v[66:69], v[74:75], off offset:512
	s_nop 0
	global_load_dwordx4 v[70:73], v[74:75], off offset:528
	v_mul_f32_e32 v61, v61, v61
	v_mul_f32_e32 v63, v63, v63
	v_mul_f32_e32 v57, v57, v57
	v_fmac_f32_e32 v61, v60, v60
	v_fmac_f32_e32 v63, v62, v62
	v_mul_f32_e32 v59, v59, v59
	v_fmac_f32_e32 v57, v56, v56
	v_add_f32_e32 v56, v61, v63
	v_fmac_f32_e32 v59, v58, v58
	v_add_f32_e32 v56, v57, v56
	v_add_f32_e32 v60, v59, v56
	s_waitcnt vmcnt(1)
	v_pk_fma_f32 v[54:55], v[54:55], 0.5, v[68:69] op_sel_hi:[1,0,1]
	v_pk_fma_f32 v[52:53], v[52:53], 0.5, v[66:67] op_sel_hi:[1,0,1]
	s_waitcnt vmcnt(0)
	v_pk_fma_f32 v[56:57], v[48:49], 0.5, v[70:71] op_sel_hi:[1,0,1]
	v_mul_f32_e32 v48, v53, v53
	v_mul_f32_e32 v49, v55, v55
	v_pk_fma_f32 v[58:59], v[50:51], 0.5, v[72:73] op_sel_hi:[1,0,1]
	v_mul_f32_e32 v50, v57, v57
	v_fmac_f32_e32 v48, v52, v52
	v_fmac_f32_e32 v49, v54, v54
	v_mul_f32_e32 v51, v59, v59
	v_fmac_f32_e32 v50, v56, v56
	v_add_f32_e32 v48, v48, v49
	v_add_f32_e32 v48, v50, v48
	v_fmac_f32_e32 v51, v58, v58
	v_add_f32_e32 v48, v51, v48
	v_add_f32_e32 v48, v60, v48
	ds_bpermute_b32 v49, v120, v48
	global_store_dwordx4 v[74:75], v[52:55], off offset:512
	global_store_dwordx4 v[74:75], v[56:59], off offset:528
	v_cvt_pk_bf16_f32 v50, v52, v53
	v_cvt_pk_bf16_f32 v51, v54, v55
	s_waitcnt lgkmcnt(0)
	v_add_f32_e32 v48, v48, v49
	ds_bpermute_b32 v49, v114, v48
	v_cvt_pk_bf16_f32 v52, v56, v57
	v_cvt_pk_bf16_f32 v53, v58, v59
	s_and_saveexec_b64 s[28:29], s[6:7]
	s_cbranch_execz .LBB0_254
	v_lshl_add_u64 v[50:51], v[64:65], 2, s[22:23]
	s_waitcnt lgkmcnt(0)
	v_add_f32_e32 v48, v48, v49
	global_atomic_add_f32 v[50:51], v48, off
.LBB0_254:
	s_or_b64 exec, exec, s[28:29]
	v_add_u32_e32 v48, 0x90, v146
	s_waitcnt lgkmcnt(0)
	v_ashrrev_i32_e32 v49, 31, v48
	v_lshlrev_b64 v[50:51], 12, v[48:49]
	v_lshl_add_u64 v[50:51], s[38:39], 0, v[50:51]
	v_lshl_add_u64 v[58:59], v[144:145], 2, v[50:51]
	global_load_dwordx4 v[50:53], v[58:59], off
	global_load_dwordx4 v[54:57], v[58:59], off offset:16
	v_lshlrev_b64 v[60:61], 11, v[48:49]
	v_lshl_add_u64 v[60:61], s[40:41], 0, v[60:61]
	v_lshl_add_u64 v[60:61], v[144:145], 1, v[60:61]
	s_waitcnt vmcnt(1)
	v_pk_fma_f32 v[46:47], v[46:47], 0.5, v[52:53] op_sel_hi:[1,0,1]
	v_pk_fma_f32 v[44:45], v[44:45], 0.5, v[50:51] op_sel_hi:[1,0,1]
	s_waitcnt vmcnt(0)
	v_pk_fma_f32 v[42:43], v[42:43], 0.5, v[56:57] op_sel_hi:[1,0,1]
	v_pk_fma_f32 v[40:41], v[40:41], 0.5, v[54:55] op_sel_hi:[1,0,1]
	global_store_dwordx4 v[58:59], v[44:47], off
	global_store_dwordx4 v[58:59], v[40:43], off offset:16
	v_cvt_pk_bf16_f32 v50, v44, v45
	v_cvt_pk_bf16_f32 v51, v46, v47
	v_cvt_pk_bf16_f32 v52, v40, v41
	v_cvt_pk_bf16_f32 v53, v42, v43
	global_load_dwordx4 v[50:53], v[58:59], off offset:512
	s_nop 0
	global_load_dwordx4 v[54:57], v[58:59], off offset:528
	v_mul_f32_e32 v45, v45, v45
	v_mul_f32_e32 v47, v47, v47
	v_mul_f32_e32 v41, v41, v41
	v_fmac_f32_e32 v45, v44, v44
	v_fmac_f32_e32 v47, v46, v46
	v_mul_f32_e32 v43, v43, v43
	v_fmac_f32_e32 v41, v40, v40
	v_add_f32_e32 v40, v45, v47
	v_fmac_f32_e32 v43, v42, v42
	v_add_f32_e32 v40, v41, v40
	v_add_f32_e32 v44, v43, v40
	s_waitcnt vmcnt(1)
	v_pk_fma_f32 v[38:39], v[38:39], 0.5, v[52:53] op_sel_hi:[1,0,1]
	v_pk_fma_f32 v[36:37], v[36:37], 0.5, v[50:51] op_sel_hi:[1,0,1]
	s_waitcnt vmcnt(0)
	v_pk_fma_f32 v[40:41], v[32:33], 0.5, v[54:55] op_sel_hi:[1,0,1]
	v_mul_f32_e32 v32, v37, v37
	v_mul_f32_e32 v33, v39, v39
	v_pk_fma_f32 v[42:43], v[34:35], 0.5, v[56:57] op_sel_hi:[1,0,1]
	v_mul_f32_e32 v34, v41, v41
	v_fmac_f32_e32 v32, v36, v36
	v_fmac_f32_e32 v33, v38, v38
	v_mul_f32_e32 v35, v43, v43
	v_fmac_f32_e32 v34, v40, v40
	v_add_f32_e32 v32, v32, v33
	v_add_f32_e32 v32, v34, v32
	v_fmac_f32_e32 v35, v42, v42
	v_add_f32_e32 v32, v35, v32
	v_add_f32_e32 v32, v44, v32
	ds_bpermute_b32 v33, v120, v32
	global_store_dwordx4 v[58:59], v[36:39], off offset:512
	global_store_dwordx4 v[58:59], v[40:43], off offset:528
	v_cvt_pk_bf16_f32 v34, v36, v37
	v_cvt_pk_bf16_f32 v35, v38, v39
	s_waitcnt lgkmcnt(0)
	v_add_f32_e32 v32, v32, v33
	ds_bpermute_b32 v33, v114, v32
	v_cvt_pk_bf16_f32 v36, v40, v41
	v_cvt_pk_bf16_f32 v37, v42, v43
	s_and_saveexec_b64 s[28:29], s[6:7]
	s_cbranch_execz .LBB0_256
	v_lshl_add_u64 v[34:35], v[48:49], 2, s[22:23]
	s_waitcnt lgkmcnt(0)
	v_add_f32_e32 v32, v32, v33
	global_atomic_add_f32 v[34:35], v32, off
.LBB0_256:
	s_or_b64 exec, exec, s[28:29]
	v_add_u32_e32 v32, 0xa0, v146
	s_waitcnt lgkmcnt(0)
	v_ashrrev_i32_e32 v33, 31, v32
	v_lshlrev_b64 v[34:35], 12, v[32:33]
	v_lshl_add_u64 v[34:35], s[38:39], 0, v[34:35]
	v_lshl_add_u64 v[42:43], v[144:145], 2, v[34:35]
	global_load_dwordx4 v[34:37], v[42:43], off
	global_load_dwordx4 v[38:41], v[42:43], off offset:16
	v_lshlrev_b64 v[44:45], 11, v[32:33]
	v_lshl_add_u64 v[44:45], s[40:41], 0, v[44:45]
	v_lshl_add_u64 v[44:45], v[144:145], 1, v[44:45]
	s_waitcnt vmcnt(1)
	v_pk_fma_f32 v[30:31], v[30:31], 0.5, v[36:37] op_sel_hi:[1,0,1]
	v_pk_fma_f32 v[28:29], v[28:29], 0.5, v[34:35] op_sel_hi:[1,0,1]
	s_waitcnt vmcnt(0)
	v_pk_fma_f32 v[26:27], v[26:27], 0.5, v[40:41] op_sel_hi:[1,0,1]
	v_pk_fma_f32 v[24:25], v[24:25], 0.5, v[38:39] op_sel_hi:[1,0,1]
	global_store_dwordx4 v[42:43], v[28:31], off
	global_store_dwordx4 v[42:43], v[24:27], off offset:16
	v_cvt_pk_bf16_f32 v34, v28, v29
	v_cvt_pk_bf16_f32 v35, v30, v31
	v_cvt_pk_bf16_f32 v36, v24, v25
	v_cvt_pk_bf16_f32 v37, v26, v27
	global_load_dwordx4 v[34:37], v[42:43], off offset:512
	s_nop 0
	global_load_dwordx4 v[38:41], v[42:43], off offset:528
	v_mul_f32_e32 v29, v29, v29
	v_mul_f32_e32 v31, v31, v31
	v_mul_f32_e32 v25, v25, v25
	v_fmac_f32_e32 v29, v28, v28
	v_fmac_f32_e32 v31, v30, v30
	v_mul_f32_e32 v27, v27, v27
	v_fmac_f32_e32 v25, v24, v24
	v_add_f32_e32 v24, v29, v31
	v_fmac_f32_e32 v27, v26, v26
	v_add_f32_e32 v24, v25, v24
	v_add_f32_e32 v28, v27, v24
	s_waitcnt vmcnt(1)
	v_pk_fma_f32 v[22:23], v[22:23], 0.5, v[36:37] op_sel_hi:[1,0,1]
	v_pk_fma_f32 v[20:21], v[20:21], 0.5, v[34:35] op_sel_hi:[1,0,1]
	s_waitcnt vmcnt(0)
	v_pk_fma_f32 v[24:25], v[16:17], 0.5, v[38:39] op_sel_hi:[1,0,1]
	v_mul_f32_e32 v16, v21, v21
	v_mul_f32_e32 v17, v23, v23
	v_pk_fma_f32 v[26:27], v[18:19], 0.5, v[40:41] op_sel_hi:[1,0,1]
	v_mul_f32_e32 v18, v25, v25
	v_fmac_f32_e32 v16, v20, v20
	v_fmac_f32_e32 v17, v22, v22
	v_mul_f32_e32 v19, v27, v27
	v_fmac_f32_e32 v18, v24, v24
	v_add_f32_e32 v16, v16, v17
	v_add_f32_e32 v16, v18, v16
	v_fmac_f32_e32 v19, v26, v26
	v_add_f32_e32 v16, v19, v16
	v_add_f32_e32 v16, v28, v16
	ds_bpermute_b32 v17, v120, v16
	global_store_dwordx4 v[42:43], v[20:23], off offset:512
	global_store_dwordx4 v[42:43], v[24:27], off offset:528
	v_cvt_pk_bf16_f32 v18, v20, v21
	v_cvt_pk_bf16_f32 v19, v22, v23
	s_waitcnt lgkmcnt(0)
	v_add_f32_e32 v16, v16, v17
	ds_bpermute_b32 v17, v114, v16
	v_cvt_pk_bf16_f32 v20, v24, v25
	v_cvt_pk_bf16_f32 v21, v26, v27
	s_and_saveexec_b64 s[28:29], s[6:7]
	s_cbranch_execz .LBB0_258
	v_lshl_add_u64 v[18:19], v[32:33], 2, s[22:23]
	s_waitcnt lgkmcnt(0)
	v_add_f32_e32 v16, v16, v17
	global_atomic_add_f32 v[18:19], v16, off
.LBB0_258:
	s_or_b64 exec, exec, s[28:29]
	v_add_u32_e32 v16, 0xb0, v146
	s_waitcnt lgkmcnt(0)
	v_ashrrev_i32_e32 v17, 31, v16
	v_lshlrev_b64 v[18:19], 12, v[16:17]
	v_lshl_add_u64 v[18:19], s[38:39], 0, v[18:19]
	v_lshl_add_u64 v[26:27], v[144:145], 2, v[18:19]
	global_load_dwordx4 v[18:21], v[26:27], off
	global_load_dwordx4 v[22:25], v[26:27], off offset:16
	v_lshlrev_b64 v[28:29], 11, v[16:17]
	v_lshl_add_u64 v[28:29], s[40:41], 0, v[28:29]
	v_lshl_add_u64 v[28:29], v[144:145], 1, v[28:29]
	s_waitcnt vmcnt(1)
	v_pk_fma_f32 v[14:15], v[14:15], 0.5, v[20:21] op_sel_hi:[1,0,1]
	v_pk_fma_f32 v[12:13], v[12:13], 0.5, v[18:19] op_sel_hi:[1,0,1]
	s_waitcnt vmcnt(0)
	v_pk_fma_f32 v[10:11], v[10:11], 0.5, v[24:25] op_sel_hi:[1,0,1]
	v_pk_fma_f32 v[8:9], v[8:9], 0.5, v[22:23] op_sel_hi:[1,0,1]
	global_store_dwordx4 v[26:27], v[12:15], off
	global_store_dwordx4 v[26:27], v[8:11], off offset:16
	v_cvt_pk_bf16_f32 v18, v12, v13
	v_cvt_pk_bf16_f32 v19, v14, v15
	v_cvt_pk_bf16_f32 v20, v8, v9
	v_cvt_pk_bf16_f32 v21, v10, v11
	global_load_dwordx4 v[18:21], v[26:27], off offset:512
	s_nop 0
	global_load_dwordx4 v[22:25], v[26:27], off offset:528
	v_mul_f32_e32 v13, v13, v13
	v_mul_f32_e32 v15, v15, v15
	v_mul_f32_e32 v9, v9, v9
	v_fmac_f32_e32 v13, v12, v12
	v_fmac_f32_e32 v15, v14, v14
	v_mul_f32_e32 v11, v11, v11
	v_fmac_f32_e32 v9, v8, v8
	v_add_f32_e32 v8, v13, v15
	v_fmac_f32_e32 v11, v10, v10
	v_add_f32_e32 v8, v9, v8
	v_add_f32_e32 v12, v11, v8
	s_waitcnt vmcnt(1)
	v_pk_fma_f32 v[6:7], v[6:7], 0.5, v[20:21] op_sel_hi:[1,0,1]
	v_pk_fma_f32 v[4:5], v[4:5], 0.5, v[18:19] op_sel_hi:[1,0,1]
	s_waitcnt vmcnt(0)
	v_pk_fma_f32 v[8:9], v[0:1], 0.5, v[22:23] op_sel_hi:[1,0,1]
	v_mul_f32_e32 v0, v5, v5
	v_mul_f32_e32 v1, v7, v7
	v_pk_fma_f32 v[10:11], v[2:3], 0.5, v[24:25] op_sel_hi:[1,0,1]
	v_mul_f32_e32 v2, v9, v9
	v_fmac_f32_e32 v0, v4, v4
	v_fmac_f32_e32 v1, v6, v6
	v_mul_f32_e32 v3, v11, v11
	v_fmac_f32_e32 v2, v8, v8
	v_add_f32_e32 v0, v0, v1
	v_add_f32_e32 v0, v2, v0
	v_fmac_f32_e32 v3, v10, v10
	v_add_f32_e32 v0, v3, v0
	v_add_f32_e32 v0, v12, v0
	ds_bpermute_b32 v1, v120, v0
	global_store_dwordx4 v[26:27], v[4:7], off offset:512
	global_store_dwordx4 v[26:27], v[8:11], off offset:528
	v_cvt_pk_bf16_f32 v2, v4, v5
	v_cvt_pk_bf16_f32 v3, v6, v7
	s_waitcnt lgkmcnt(0)
	v_add_f32_e32 v0, v0, v1
	ds_bpermute_b32 v1, v114, v0
	v_cvt_pk_bf16_f32 v4, v8, v9
	v_cvt_pk_bf16_f32 v5, v10, v11
	s_and_saveexec_b64 s[28:29], s[6:7]
	s_cbranch_execz .LBB0_231
	v_lshl_add_u64 v[2:3], v[16:17], 2, s[22:23]
	s_waitcnt lgkmcnt(0)
	v_add_f32_e32 v0, v0, v1
	global_atomic_add_f32 v[2:3], v0, off
	s_branch .LBB0_231

.LBB0_263:
	v_and_b32_e32 v160, 15, v174
	v_bfe_u32 v161, v174, 4, 2
	v_lshrrev_b32_e32 v162, 6, v174
	v_and_b32_e32 v136, 63, v174
	v_readfirstlane_b32 s80, v162
	s_lshr_b32 s81, s33, 8
	s_lshr_b32 s82, s33, 3
	s_and_b32 s82, s82, 31
	s_mul_i32 s83, s80, 704
	v_lshlrev_b32_e32 v164, 4, v161
	v_mov_b32_e32 v167, 0
	s_lshl_b32 s84, s82, 5
	v_add_u32_e32 v165, s84, v160
	v_mul_u32_u24_e32 v166, 0x1600, v165
	v_add3_u32 v166, v166, v164, s83
	s_add_u32 s86, s74, 0x2c00000
	s_addc_u32 s87, s75, 0
	s_mov_b32 s88, 0x16000
	s_mov_b32 s89, 0
	v_lshl_add_u64 v[152:153], s[86:87], 0, v[166:167]
	v_lshl_add_u64 v[154:155], v[152:153], 0, s[88:89]
	s_lshl_b32 s84, s81, 5
	v_add_u32_e32 v165, s84, v160
	v_mul_u32_u24_e32 v166, 0x1600, v165
	v_add3_u32 v166, v166, v164, s83
	s_add_u32 s90, s74, 0x10980000
	s_addc_u32 s91, s75, 0
	v_lshl_add_u64 v[156:157], s[90:91], 0, v[166:167]
	v_lshl_add_u64 v[158:159], v[156:157], 0, s[88:89]
	v_mov_b32_e32 v128, 0
	v_mov_b32_e32 v129, 0
	v_mov_b32_e32 v130, 0
	v_mov_b32_e32 v131, 0
	v_mov_b32_e32 v132, 0
	v_mov_b32_e32 v133, 0
	v_mov_b32_e32 v134, 0
	v_mov_b32_e32 v135, 0
	v_mov_b32_e32 v144, 0
	v_mov_b32_e32 v145, 0
	v_mov_b32_e32 v146, 0
	v_mov_b32_e32 v147, 0
	v_mov_b32_e32 v148, 0
	v_mov_b32_e32 v149, 0
	v_mov_b32_e32 v150, 0
	v_mov_b32_e32 v151, 0
	global_load_dwordx4 v[0:3], v[152:153], off
	global_load_dwordx4 v[4:7], v[154:155], off
	global_load_dwordx4 v[8:11], v[156:157], off
	global_load_dwordx4 v[12:15], v[158:159], off
	global_load_dwordx4 v[16:19], v[152:153], off offset:64
	global_load_dwordx4 v[20:23], v[154:155], off offset:64
	global_load_dwordx4 v[24:27], v[156:157], off offset:64
	global_load_dwordx4 v[28:31], v[158:159], off offset:64
	global_load_dwordx4 v[32:35], v[152:153], off offset:128
	global_load_dwordx4 v[36:39], v[154:155], off offset:128
	global_load_dwordx4 v[40:43], v[156:157], off offset:128
	global_load_dwordx4 v[44:47], v[158:159], off offset:128
	global_load_dwordx4 v[48:51], v[152:153], off offset:192
	global_load_dwordx4 v[52:55], v[154:155], off offset:192
	global_load_dwordx4 v[56:59], v[156:157], off offset:192
	global_load_dwordx4 v[60:63], v[158:159], off offset:192
	global_load_dwordx4 v[64:67], v[152:153], off offset:256
	global_load_dwordx4 v[68:71], v[154:155], off offset:256
	global_load_dwordx4 v[72:75], v[156:157], off offset:256
	global_load_dwordx4 v[76:79], v[158:159], off offset:256
	global_load_dwordx4 v[80:83], v[152:153], off offset:320
	global_load_dwordx4 v[84:87], v[154:155], off offset:320
	global_load_dwordx4 v[88:91], v[156:157], off offset:320
	global_load_dwordx4 v[92:95], v[158:159], off offset:320
	global_load_dwordx4 v[96:99], v[152:153], off offset:384
	global_load_dwordx4 v[100:103], v[154:155], off offset:384
	global_load_dwordx4 v[104:107], v[156:157], off offset:384
	global_load_dwordx4 v[108:111], v[158:159], off offset:384
	global_load_dwordx4 v[112:115], v[152:153], off offset:448
	global_load_dwordx4 v[116:119], v[154:155], off offset:448
	global_load_dwordx4 v[120:123], v[156:157], off offset:448
	global_load_dwordx4 v[124:127], v[158:159], off offset:448
	s_waitcnt vmcnt(16)
	v_mfma_f32_16x16x32_bf16 v[128:131], v[0:3], v[8:11], v[128:131]
	v_mfma_f32_16x16x32_bf16 v[132:135], v[4:7], v[8:11], v[132:135]
	v_mfma_f32_16x16x32_bf16 v[144:147], v[0:3], v[12:15], v[144:147]
	v_mfma_f32_16x16x32_bf16 v[148:151], v[4:7], v[12:15], v[148:151]
	v_mfma_f32_16x16x32_bf16 v[128:131], v[16:19], v[24:27], v[128:131]
	v_mfma_f32_16x16x32_bf16 v[132:135], v[20:23], v[24:27], v[132:135]
	v_mfma_f32_16x16x32_bf16 v[144:147], v[16:19], v[28:31], v[144:147]
	v_mfma_f32_16x16x32_bf16 v[148:151], v[20:23], v[28:31], v[148:151]
	v_mfma_f32_16x16x32_bf16 v[128:131], v[32:35], v[40:43], v[128:131]
	v_mfma_f32_16x16x32_bf16 v[132:135], v[36:39], v[40:43], v[132:135]
	v_mfma_f32_16x16x32_bf16 v[144:147], v[32:35], v[44:47], v[144:147]
	v_mfma_f32_16x16x32_bf16 v[148:151], v[36:39], v[44:47], v[148:151]
	v_mfma_f32_16x16x32_bf16 v[128:131], v[48:51], v[56:59], v[128:131]
	v_mfma_f32_16x16x32_bf16 v[132:135], v[52:55], v[56:59], v[132:135]
	v_mfma_f32_16x16x32_bf16 v[144:147], v[48:51], v[60:63], v[144:147]
	v_mfma_f32_16x16x32_bf16 v[148:151], v[52:55], v[60:63], v[148:151]
	global_load_dwordx4 v[0:3], v[152:153], off offset:512
	global_load_dwordx4 v[4:7], v[154:155], off offset:512
	global_load_dwordx4 v[8:11], v[156:157], off offset:512
	global_load_dwordx4 v[12:15], v[158:159], off offset:512
	global_load_dwordx4 v[16:19], v[152:153], off offset:576
	global_load_dwordx4 v[20:23], v[154:155], off offset:576
	global_load_dwordx4 v[24:27], v[156:157], off offset:576
	global_load_dwordx4 v[28:31], v[158:159], off offset:576
	global_load_dwordx4 v[32:35], v[152:153], off offset:640
	global_load_dwordx4 v[36:39], v[154:155], off offset:640
	global_load_dwordx4 v[40:43], v[156:157], off offset:640
	global_load_dwordx4 v[44:47], v[158:159], off offset:640
	s_waitcnt vmcnt(12)
	v_mfma_f32_16x16x32_bf16 v[128:131], v[64:67], v[72:75], v[128:131]
	v_mfma_f32_16x16x32_bf16 v[132:135], v[68:71], v[72:75], v[132:135]
	v_mfma_f32_16x16x32_bf16 v[144:147], v[64:67], v[76:79], v[144:147]
	v_mfma_f32_16x16x32_bf16 v[148:151], v[68:71], v[76:79], v[148:151]
	v_mfma_f32_16x16x32_bf16 v[128:131], v[80:83], v[88:91], v[128:131]
	v_mfma_f32_16x16x32_bf16 v[132:135], v[84:87], v[88:91], v[132:135]
	v_mfma_f32_16x16x32_bf16 v[144:147], v[80:83], v[92:95], v[144:147]
	v_mfma_f32_16x16x32_bf16 v[148:151], v[84:87], v[92:95], v[148:151]
	v_mfma_f32_16x16x32_bf16 v[128:131], v[96:99], v[104:107], v[128:131]
	v_mfma_f32_16x16x32_bf16 v[132:135], v[100:103], v[104:107], v[132:135]
	v_mfma_f32_16x16x32_bf16 v[144:147], v[96:99], v[108:111], v[144:147]
	v_mfma_f32_16x16x32_bf16 v[148:151], v[100:103], v[108:111], v[148:151]
	v_mfma_f32_16x16x32_bf16 v[128:131], v[112:115], v[120:123], v[128:131]
	v_mfma_f32_16x16x32_bf16 v[132:135], v[116:119], v[120:123], v[132:135]
	v_mfma_f32_16x16x32_bf16 v[144:147], v[112:115], v[124:127], v[144:147]
	v_mfma_f32_16x16x32_bf16 v[148:151], v[116:119], v[124:127], v[148:151]
	s_waitcnt vmcnt(0)
	v_mfma_f32_16x16x32_bf16 v[128:131], v[0:3], v[8:11], v[128:131]
	v_mfma_f32_16x16x32_bf16 v[132:135], v[4:7], v[8:11], v[132:135]
	v_mfma_f32_16x16x32_bf16 v[144:147], v[0:3], v[12:15], v[144:147]
	v_mfma_f32_16x16x32_bf16 v[148:151], v[4:7], v[12:15], v[148:151]
	v_mfma_f32_16x16x32_bf16 v[128:131], v[16:19], v[24:27], v[128:131]
	v_mfma_f32_16x16x32_bf16 v[132:135], v[20:23], v[24:27], v[132:135]
	v_mfma_f32_16x16x32_bf16 v[144:147], v[16:19], v[28:31], v[144:147]
	v_mfma_f32_16x16x32_bf16 v[148:151], v[20:23], v[28:31], v[148:151]
	v_mfma_f32_16x16x32_bf16 v[128:131], v[32:35], v[40:43], v[128:131]
	v_mfma_f32_16x16x32_bf16 v[132:135], v[36:39], v[40:43], v[132:135]
	v_mfma_f32_16x16x32_bf16 v[144:147], v[32:35], v[44:47], v[144:147]
	v_mfma_f32_16x16x32_bf16 v[148:151], v[36:39], v[44:47], v[148:151]
	s_nop 7
	s_nop 7
	v_lshlrev_b32_e32 v170, 12, v162
	v_lshl_add_u32 v170, v136, 4, v170
	ds_write_b128 v170, v[128:131]
	ds_write_b128 v170, v[132:135] offset:1024
	ds_write_b128 v170, v[144:147] offset:2048
	ds_write_b128 v170, v[148:151] offset:3072
	s_waitcnt lgkmcnt(0)
	s_barrier
	s_cmp_ge_u32 s80, 4
	s_cbranch_scc1 .Lmg1_end
	s_lshl_b32 s84, s80, 10
	v_lshlrev_b32_e32 v171, 4, v136
	v_add_u32_e32 v171, s84, v171
	ds_read_b128 v[0:3], v171
	ds_read_b128 v[4:7], v171 offset:4096
	ds_read_b128 v[8:11], v171 offset:8192
	ds_read_b128 v[12:15], v171 offset:12288
	ds_read_b128 v[16:19], v171 offset:16384
	ds_read_b128 v[20:23], v171 offset:20480
	ds_read_b128 v[24:27], v171 offset:24576
	ds_read_b128 v[28:31], v171 offset:28672
	s_lshr_b32 s84, s80, 1
	s_lshl_b32 s84, s84, 4
	s_lshl_b32 s85, s81, 5
	s_add_i32 s84, s84, s85
	s_addk_i32 s84, 0x4000
	s_and_b32 s85, s80, 1
	s_lshl_b32 s85, s85, 4
	s_lshl_b32 s83, s82, 5
	s_add_i32 s85, s85, s83
	v_add_u32_e32 v165, s84, v160
	v_lshl_add_u32 v164, v161, 2, s85
	v_lshlrev_b32_e32 v166, 12, v165
	v_lshl_add_u32 v166, v164, 2, v166
	v_mov_b32_e32 v167, 0
	s_add_u32 s86, s74, 0x5000000
	s_addc_u32 s87, s75, 0
	v_lshl_add_u64 v[168:169], s[86:87], 0, v[166:167]
	global_load_dwordx4 v[32:35], v[168:169], off
	v_lshrrev_b32_e32 v172, 1, v166
	v_mov_b32_e32 v173, 0
	s_add_u32 s86, s74, 0x9100000
	s_addc_u32 s87, s75, 0
	v_lshl_add_u64 v[172:173], s[86:87], 0, v[172:173]
	v_lshlrev_b32_e32 v166, 2, v165
	s_add_u32 s86, s74, 0x12b70400
	s_addc_u32 s87, s75, 0
	v_lshl_add_u64 v[166:167], s[86:87], 0, v[166:167]
	s_waitcnt lgkmcnt(0)
	v_add_f32_e32 v0, v0, v4
	v_add_f32_e32 v1, v1, v5
	v_add_f32_e32 v2, v2, v6
	v_add_f32_e32 v3, v3, v7
	v_add_f32_e32 v0, v0, v8
	v_add_f32_e32 v1, v1, v9
	v_add_f32_e32 v2, v2, v10
	v_add_f32_e32 v3, v3, v11
	v_add_f32_e32 v0, v0, v12
	v_add_f32_e32 v1, v1, v13
	v_add_f32_e32 v2, v2, v14
	v_add_f32_e32 v3, v3, v15
	v_add_f32_e32 v0, v0, v16
	v_add_f32_e32 v1, v1, v17
	v_add_f32_e32 v2, v2, v18
	v_add_f32_e32 v3, v3, v19
	v_add_f32_e32 v0, v0, v20
	v_add_f32_e32 v1, v1, v21
	v_add_f32_e32 v2, v2, v22
	v_add_f32_e32 v3, v3, v23
	v_add_f32_e32 v0, v0, v24
	v_add_f32_e32 v1, v1, v25
	v_add_f32_e32 v2, v2, v26
	v_add_f32_e32 v3, v3, v27
	v_add_f32_e32 v0, v0, v28
	v_add_f32_e32 v1, v1, v29
	v_add_f32_e32 v2, v2, v30
	v_add_f32_e32 v3, v3, v31
	s_waitcnt vmcnt(0)
	v_fma_f32 v32, v0, 0.5, v32
	v_fma_f32 v33, v1, 0.5, v33
	v_fma_f32 v34, v2, 0.5, v34
	v_fma_f32 v35, v3, 0.5, v35
	global_store_dwordx4 v[168:169], v[32:35], off
	v_cvt_pk_bf16_f32 v36, v32, v33
	v_cvt_pk_bf16_f32 v37, v34, v35
	v_mul_f32_e32 v38, v32, v32
	v_fmac_f32_e32 v38, v33, v33
	v_fmac_f32_e32 v38, v34, v34
	v_fmac_f32_e32 v38, v35, v35
	v_xor_b32_e32 v39, 16, v136
	v_lshlrev_b32_e32 v39, 2, v39
	ds_bpermute_b32 v40, v39, v38
	v_xor_b32_e32 v41, 32, v136
	v_lshlrev_b32_e32 v41, 2, v41
	s_waitcnt lgkmcnt(0)
	v_add_f32_e32 v38, v38, v40
	ds_bpermute_b32 v40, v41, v38
	s_waitcnt lgkmcnt(0)
	v_add_f32_e32 v38, v38, v40
	v_cmp_gt_u32_e64 s[82:83], 16, v136
	s_nop 1
	s_and_saveexec_b64 s[84:85], s[82:83]
	global_atomic_add_f32 v[166:167], v38, off
	s_mov_b64 exec, s[84:85]

.LBB0_1503:
	ds_read_b128 v[144:147], v151
	ds_read_b128 v[156:159], v151 offset:1024
	ds_read_b128 v[160:163], v151 offset:2048
	ds_read_b128 v[164:167], v151 offset:3072
	s_add_u32 s20, s18, 0x100
	s_addc_u32 s21, s19, 0
	s_cmp_eq_u32 s53, 40
	s_cselect_b32 s25, s9, s21
	s_cselect_b32 s24, s8, s20
	s_cselect_b32 s23, s11, s52
	s_cselect_b32 s22, s10, s51
	v_lshl_add_u64 v[172:173], s[18:19], 0, v[136:137]
	s_add_i32 m0, s29, 0xc000
	ds_read_b128 v[168:171], v152
	ds_read_b128 v[178:181], v152 offset:1024
	ds_read_b128 v[182:185], v152 offset:2048
	ds_read_b128 v[186:189], v152 offset:3072
	ds_read_b128 v[190:193], v152 offset:4096
	ds_read_b128 v[194:197], v152 offset:5120
	ds_read_b128 v[198:201], v152 offset:6144
	ds_read_b128 v[202:205], v152 offset:7168
	global_load_lds_dwordx4 v[172:173], off
	v_lshl_add_u64 v[172:173], s[18:19], 0, v[138:139]
	s_add_i32 m0, s29, 0xe000
	s_nop 0
	global_load_lds_dwordx4 v[172:173], off
	s_waitcnt lgkmcnt(8)
	s_barrier
	s_waitcnt lgkmcnt(0)
	s_setprio 1
	s_waitcnt lgkmcnt(0)
	v_mfma_f32_16x16x32_bf16 v[124:127], v[144:147], v[168:171], v[124:127]
	v_mfma_f32_16x16x32_bf16 v[120:123], v[160:163], v[168:171], v[120:123]
	v_mfma_f32_16x16x32_bf16 v[108:111], v[144:147], v[182:185], v[108:111]
	v_mfma_f32_16x16x32_bf16 v[104:107], v[160:163], v[182:185], v[104:107]
	v_mfma_f32_16x16x32_bf16 v[92:95], v[144:147], v[190:193], v[92:95]
	v_mfma_f32_16x16x32_bf16 v[88:91], v[160:163], v[190:193], v[88:91]
	v_mfma_f32_16x16x32_bf16 v[76:79], v[144:147], v[198:201], v[76:79]
	v_mfma_f32_16x16x32_bf16 v[72:75], v[160:163], v[198:201], v[72:75]
	v_mfma_f32_16x16x32_bf16 v[124:127], v[156:159], v[178:181], v[124:127]
	v_mfma_f32_16x16x32_bf16 v[120:123], v[164:167], v[178:181], v[120:123]
	v_mfma_f32_16x16x32_bf16 v[108:111], v[156:159], v[186:189], v[108:111]
	v_mfma_f32_16x16x32_bf16 v[104:107], v[164:167], v[186:189], v[104:107]
	v_mfma_f32_16x16x32_bf16 v[92:95], v[156:159], v[194:197], v[92:95]
	v_mfma_f32_16x16x32_bf16 v[88:91], v[164:167], v[194:197], v[88:91]
	v_mfma_f32_16x16x32_bf16 v[76:79], v[156:159], v[202:205], v[76:79]
	v_mfma_f32_16x16x32_bf16 v[72:75], v[164:167], v[202:205], v[72:75]
	s_setprio 0
	s_barrier
	s_add_i32 s18, s43, s28
	v_lshl_add_u64 v[172:173], s[22:23], 0, v[130:131]
	s_mov_b32 m0, s18
	ds_read_b128 v[206:209], v153
	ds_read_b128 v[210:213], v153 offset:1024
	ds_read_b128 v[214:217], v153 offset:2048
	ds_read_b128 v[218:221], v153 offset:3072
	global_load_lds_dwordx4 v[172:173], off
	v_lshl_add_u64 v[222:223], s[22:23], 0, v[134:135]
	s_add_i32 m0, s18, 0x2000
	s_nop 0
	global_load_lds_dwordx4 v[222:223], off
	s_barrier
	s_waitcnt lgkmcnt(0)
	s_setprio 1
	s_waitcnt lgkmcnt(0)
	v_mfma_f32_16x16x32_bf16 v[116:119], v[206:209], v[168:171], v[116:119]
	v_mfma_f32_16x16x32_bf16 v[112:115], v[214:217], v[168:171], v[112:115]
	v_mfma_f32_16x16x32_bf16 v[100:103], v[206:209], v[182:185], v[100:103]
	v_mfma_f32_16x16x32_bf16 v[96:99], v[214:217], v[182:185], v[96:99]
	v_mfma_f32_16x16x32_bf16 v[84:87], v[206:209], v[190:193], v[84:87]
	v_mfma_f32_16x16x32_bf16 v[80:83], v[214:217], v[190:193], v[80:83]
	v_mfma_f32_16x16x32_bf16 v[68:71], v[206:209], v[198:201], v[68:71]
	v_mfma_f32_16x16x32_bf16 v[64:67], v[214:217], v[198:201], v[64:67]
	v_mfma_f32_16x16x32_bf16 v[116:119], v[210:213], v[178:181], v[116:119]
	v_mfma_f32_16x16x32_bf16 v[112:115], v[218:221], v[178:181], v[112:115]
	v_mfma_f32_16x16x32_bf16 v[100:103], v[210:213], v[186:189], v[100:103]
	v_mfma_f32_16x16x32_bf16 v[96:99], v[218:221], v[186:189], v[96:99]
	v_mfma_f32_16x16x32_bf16 v[84:87], v[210:213], v[194:197], v[84:87]
	v_mfma_f32_16x16x32_bf16 v[80:83], v[218:221], v[194:197], v[80:83]
	v_mfma_f32_16x16x32_bf16 v[68:71], v[210:213], v[202:205], v[68:71]
	v_mfma_f32_16x16x32_bf16 v[64:67], v[218:221], v[202:205], v[64:67]
	s_setprio 0
	s_mov_b32 m0, s29
	v_lshl_add_u64 v[224:225], s[24:25], 0, v[128:129]
	s_barrier
	ds_read_b128 v[168:171], v152 offset:16384
	ds_read_b128 v[178:181], v152 offset:17408
	ds_read_b128 v[182:185], v152 offset:18432
	ds_read_b128 v[186:189], v152 offset:19456
	ds_read_b128 v[190:193], v152 offset:20480
	ds_read_b128 v[194:197], v152 offset:21504
	ds_read_b128 v[198:201], v152 offset:22528
	ds_read_b128 v[202:205], v152 offset:23552
	global_load_lds_dwordx4 v[224:225], off
	v_lshl_add_u64 v[226:227], s[24:25], 0, v[132:133]
	s_mov_b32 m0, s30
	s_nop 0
	global_load_lds_dwordx4 v[226:227], off
	s_barrier
	s_waitcnt lgkmcnt(0)
	s_setprio 1
	s_waitcnt lgkmcnt(0)
	v_mfma_f32_16x16x32_bf16 v[60:63], v[144:147], v[168:171], v[60:63]
	v_mfma_f32_16x16x32_bf16 v[56:59], v[160:163], v[168:171], v[56:59]
	v_mfma_f32_16x16x32_bf16 v[44:47], v[144:147], v[182:185], v[44:47]
	v_mfma_f32_16x16x32_bf16 v[40:43], v[160:163], v[182:185], v[40:43]
	v_mfma_f32_16x16x32_bf16 v[28:31], v[144:147], v[190:193], v[28:31]
	v_mfma_f32_16x16x32_bf16 v[24:27], v[160:163], v[190:193], v[24:27]
	v_mfma_f32_16x16x32_bf16 v[12:15], v[144:147], v[198:201], v[12:15]
	v_mfma_f32_16x16x32_bf16 v[8:11], v[160:163], v[198:201], v[8:11]
	v_mfma_f32_16x16x32_bf16 v[60:63], v[156:159], v[178:181], v[60:63]
	v_mfma_f32_16x16x32_bf16 v[56:59], v[164:167], v[178:181], v[56:59]
	v_mfma_f32_16x16x32_bf16 v[44:47], v[156:159], v[186:189], v[44:47]
	v_mfma_f32_16x16x32_bf16 v[40:43], v[164:167], v[186:189], v[40:43]
	v_mfma_f32_16x16x32_bf16 v[28:31], v[156:159], v[194:197], v[28:31]
	v_mfma_f32_16x16x32_bf16 v[24:27], v[164:167], v[194:197], v[24:27]
	v_mfma_f32_16x16x32_bf16 v[12:15], v[156:159], v[202:205], v[12:15]
	v_mfma_f32_16x16x32_bf16 v[8:11], v[164:167], v[202:205], v[8:11]
	s_setprio 0
	s_barrier
	s_add_u32 s18, s22, 0xb0000
	s_addc_u32 s19, s23, 0
	s_add_i32 s54, s46, s28
	v_lshl_add_u64 v[144:145], s[18:19], 0, v[130:131]
	s_mov_b32 m0, s54
	s_nop 0
	global_load_lds_dwordx4 v[144:145], off
	v_lshl_add_u64 v[144:145], s[18:19], 0, v[134:135]
	s_add_i32 m0, s54, 0x2000
	s_nop 0
	global_load_lds_dwordx4 v[144:145], off
	s_waitcnt vmcnt(6)
	s_barrier
	s_setprio 1
	v_mfma_f32_16x16x32_bf16 v[52:55], v[206:209], v[168:171], v[52:55]
	v_mfma_f32_16x16x32_bf16 v[48:51], v[214:217], v[168:171], v[48:51]
	v_mfma_f32_16x16x32_bf16 v[36:39], v[206:209], v[182:185], v[36:39]
	v_mfma_f32_16x16x32_bf16 v[32:35], v[214:217], v[182:185], v[32:35]
	v_mfma_f32_16x16x32_bf16 v[20:23], v[206:209], v[190:193], v[20:23]
	v_mfma_f32_16x16x32_bf16 v[16:19], v[214:217], v[190:193], v[16:19]
	v_mfma_f32_16x16x32_bf16 v[4:7], v[206:209], v[198:201], v[4:7]
	v_mfma_f32_16x16x32_bf16 v[0:3], v[214:217], v[198:201], v[0:3]
	v_mfma_f32_16x16x32_bf16 v[52:55], v[210:213], v[178:181], v[52:55]
	v_mfma_f32_16x16x32_bf16 v[48:51], v[218:221], v[178:181], v[48:51]
	v_mfma_f32_16x16x32_bf16 v[36:39], v[210:213], v[186:189], v[36:39]
	v_mfma_f32_16x16x32_bf16 v[32:35], v[218:221], v[186:189], v[32:35]
	v_mfma_f32_16x16x32_bf16 v[20:23], v[210:213], v[194:197], v[20:23]
	v_mfma_f32_16x16x32_bf16 v[16:19], v[218:221], v[194:197], v[16:19]
	v_mfma_f32_16x16x32_bf16 v[4:7], v[210:213], v[202:205], v[4:7]
	v_mfma_f32_16x16x32_bf16 v[0:3], v[218:221], v[202:205], v[0:3]
	s_setprio 0
	s_add_i32 s54, 0, 0x18000
	v_add_u32_e32 v155, s54, v149
	s_barrier
	ds_read_b128 v[144:147], v155
	ds_read_b128 v[156:159], v155 offset:1024
	ds_read_b128 v[160:163], v155 offset:2048
	ds_read_b128 v[164:167], v155 offset:3072
	s_add_u32 s18, s24, 0xb0000
	s_addc_u32 s19, s25, 0
	s_mov_b32 m0, s31
	v_lshl_add_u64 v[206:207], s[18:19], 0, v[128:129]
	ds_read_b128 v[168:171], v152 offset:32768
	ds_read_b128 v[178:181], v152 offset:33792
	ds_read_b128 v[182:185], v152 offset:34816
	ds_read_b128 v[186:189], v152 offset:35840
	ds_read_b128 v[190:193], v152 offset:36864
	ds_read_b128 v[194:197], v152 offset:37888
	ds_read_b128 v[198:201], v152 offset:38912
	ds_read_b128 v[202:205], v152 offset:39936
	global_load_lds_dwordx4 v[206:207], off
	v_lshl_add_u64 v[206:207], s[18:19], 0, v[132:133]
	s_mov_b32 m0, s34
	s_nop 0
	global_load_lds_dwordx4 v[206:207], off
	s_waitcnt lgkmcnt(8)
	s_barrier
	s_waitcnt lgkmcnt(0)
	s_setprio 1
	s_waitcnt lgkmcnt(0)
	v_mfma_f32_16x16x32_bf16 v[124:127], v[144:147], v[168:171], v[124:127]
	v_mfma_f32_16x16x32_bf16 v[120:123], v[160:163], v[168:171], v[120:123]
	v_mfma_f32_16x16x32_bf16 v[108:111], v[144:147], v[182:185], v[108:111]
	v_mfma_f32_16x16x32_bf16 v[104:107], v[160:163], v[182:185], v[104:107]
	v_mfma_f32_16x16x32_bf16 v[92:95], v[144:147], v[190:193], v[92:95]
	v_mfma_f32_16x16x32_bf16 v[88:91], v[160:163], v[190:193], v[88:91]
	v_mfma_f32_16x16x32_bf16 v[76:79], v[144:147], v[198:201], v[76:79]
	v_mfma_f32_16x16x32_bf16 v[72:75], v[160:163], v[198:201], v[72:75]
	v_mfma_f32_16x16x32_bf16 v[124:127], v[156:159], v[178:181], v[124:127]
	v_mfma_f32_16x16x32_bf16 v[120:123], v[164:167], v[178:181], v[120:123]
	v_mfma_f32_16x16x32_bf16 v[108:111], v[156:159], v[186:189], v[108:111]
	v_mfma_f32_16x16x32_bf16 v[104:107], v[164:167], v[186:189], v[104:107]
	v_mfma_f32_16x16x32_bf16 v[92:95], v[156:159], v[194:197], v[92:95]
	v_mfma_f32_16x16x32_bf16 v[88:91], v[164:167], v[194:197], v[88:91]
	v_mfma_f32_16x16x32_bf16 v[76:79], v[156:159], v[202:205], v[76:79]
	v_mfma_f32_16x16x32_bf16 v[72:75], v[164:167], v[202:205], v[72:75]
	s_setprio 0
	s_barrier
	s_add_i32 s24, 0, 0x1c000
	s_add_i32 s18, s54, s28
	v_add_u32_e32 v155, s24, v149
	v_lshl_add_u64 v[172:173], v[172:173], 0, s[14:15]
	s_mov_b32 m0, s18
	ds_read_b128 v[206:209], v155
	ds_read_b128 v[210:213], v155 offset:1024
	ds_read_b128 v[214:217], v155 offset:2048
	ds_read_b128 v[218:221], v155 offset:3072
	global_load_lds_dwordx4 v[172:173], off
	v_lshl_add_u64 v[172:173], v[222:223], 0, s[14:15]
	s_add_i32 m0, s18, 0x2000
	s_nop 0
	global_load_lds_dwordx4 v[172:173], off
	s_barrier
	s_waitcnt lgkmcnt(0)
	s_setprio 1
	s_waitcnt lgkmcnt(0)
	v_mfma_f32_16x16x32_bf16 v[116:119], v[206:209], v[168:171], v[116:119]
	v_mfma_f32_16x16x32_bf16 v[112:115], v[214:217], v[168:171], v[112:115]
	v_mfma_f32_16x16x32_bf16 v[100:103], v[206:209], v[182:185], v[100:103]
	v_mfma_f32_16x16x32_bf16 v[96:99], v[214:217], v[182:185], v[96:99]
	v_mfma_f32_16x16x32_bf16 v[84:87], v[206:209], v[190:193], v[84:87]
	v_mfma_f32_16x16x32_bf16 v[80:83], v[214:217], v[190:193], v[80:83]
	v_mfma_f32_16x16x32_bf16 v[68:71], v[206:209], v[198:201], v[68:71]
	v_mfma_f32_16x16x32_bf16 v[64:67], v[214:217], v[198:201], v[64:67]
	v_mfma_f32_16x16x32_bf16 v[116:119], v[210:213], v[178:181], v[116:119]
	v_mfma_f32_16x16x32_bf16 v[112:115], v[218:221], v[178:181], v[112:115]
	v_mfma_f32_16x16x32_bf16 v[100:103], v[210:213], v[186:189], v[100:103]
	v_mfma_f32_16x16x32_bf16 v[96:99], v[218:221], v[186:189], v[96:99]
	v_mfma_f32_16x16x32_bf16 v[84:87], v[210:213], v[194:197], v[84:87]
	v_mfma_f32_16x16x32_bf16 v[80:83], v[218:221], v[194:197], v[80:83]
	v_mfma_f32_16x16x32_bf16 v[68:71], v[210:213], v[202:205], v[68:71]
	v_mfma_f32_16x16x32_bf16 v[64:67], v[218:221], v[202:205], v[64:67]
	s_setprio 0
	s_mov_b32 m0, s36
	v_lshl_add_u64 v[172:173], v[224:225], 0, s[14:15]
	s_barrier
	ds_read_b128 v[168:171], v152 offset:49152
	ds_read_b128 v[178:181], v152 offset:50176
	ds_read_b128 v[182:185], v152 offset:51200
	ds_read_b128 v[186:189], v152 offset:52224
	ds_read_b128 v[190:193], v152 offset:53248
	ds_read_b128 v[194:197], v152 offset:54272
	ds_read_b128 v[198:201], v152 offset:55296
	ds_read_b128 v[202:205], v152 offset:56320
	global_load_lds_dwordx4 v[172:173], off
	v_lshl_add_u64 v[172:173], v[226:227], 0, s[14:15]
	s_mov_b32 m0, s37
	s_nop 0
	global_load_lds_dwordx4 v[172:173], off
	s_barrier
	s_waitcnt lgkmcnt(0)
	s_setprio 1
	s_waitcnt lgkmcnt(0)
	v_mfma_f32_16x16x32_bf16 v[60:63], v[144:147], v[168:171], v[60:63]
	v_mfma_f32_16x16x32_bf16 v[56:59], v[160:163], v[168:171], v[56:59]
	v_mfma_f32_16x16x32_bf16 v[44:47], v[144:147], v[182:185], v[44:47]
	v_mfma_f32_16x16x32_bf16 v[40:43], v[160:163], v[182:185], v[40:43]
	v_mfma_f32_16x16x32_bf16 v[28:31], v[144:147], v[190:193], v[28:31]
	v_mfma_f32_16x16x32_bf16 v[24:27], v[160:163], v[190:193], v[24:27]
	v_mfma_f32_16x16x32_bf16 v[12:15], v[144:147], v[198:201], v[12:15]
	v_mfma_f32_16x16x32_bf16 v[8:11], v[160:163], v[198:201], v[8:11]
	v_mfma_f32_16x16x32_bf16 v[60:63], v[156:159], v[178:181], v[60:63]
	v_mfma_f32_16x16x32_bf16 v[56:59], v[164:167], v[178:181], v[56:59]
	v_mfma_f32_16x16x32_bf16 v[44:47], v[156:159], v[186:189], v[44:47]
	v_mfma_f32_16x16x32_bf16 v[40:43], v[164:167], v[186:189], v[40:43]
	v_mfma_f32_16x16x32_bf16 v[28:31], v[156:159], v[194:197], v[28:31]
	v_mfma_f32_16x16x32_bf16 v[24:27], v[164:167], v[194:197], v[24:27]
	v_mfma_f32_16x16x32_bf16 v[12:15], v[156:159], v[202:205], v[12:15]
	v_mfma_f32_16x16x32_bf16 v[8:11], v[164:167], v[202:205], v[8:11]
	s_setprio 0
	s_barrier
	s_add_u32 s18, s22, 0xb0080
	s_addc_u32 s19, s23, 0
	s_add_i32 s22, s24, s28
	v_lshl_add_u64 v[144:145], s[18:19], 0, v[130:131]
	s_mov_b32 m0, s22
	s_nop 0
	global_load_lds_dwordx4 v[144:145], off
	v_lshl_add_u64 v[144:145], s[18:19], 0, v[134:135]
	s_add_i32 m0, s22, 0x2000
	s_nop 0
	global_load_lds_dwordx4 v[144:145], off
	s_waitcnt vmcnt(6)
	s_barrier
	s_setprio 1
	v_mfma_f32_16x16x32_bf16 v[52:55], v[206:209], v[168:171], v[52:55]
	v_mfma_f32_16x16x32_bf16 v[48:51], v[214:217], v[168:171], v[48:51]
	v_mfma_f32_16x16x32_bf16 v[36:39], v[206:209], v[182:185], v[36:39]
	v_mfma_f32_16x16x32_bf16 v[32:35], v[214:217], v[182:185], v[32:35]
	v_mfma_f32_16x16x32_bf16 v[20:23], v[206:209], v[190:193], v[20:23]
	v_mfma_f32_16x16x32_bf16 v[16:19], v[214:217], v[190:193], v[16:19]
	v_mfma_f32_16x16x32_bf16 v[4:7], v[206:209], v[198:201], v[4:7]
	v_mfma_f32_16x16x32_bf16 v[0:3], v[214:217], v[198:201], v[0:3]
	v_mfma_f32_16x16x32_bf16 v[52:55], v[210:213], v[178:181], v[52:55]
	v_mfma_f32_16x16x32_bf16 v[48:51], v[218:221], v[178:181], v[48:51]
	v_mfma_f32_16x16x32_bf16 v[36:39], v[210:213], v[186:189], v[36:39]
	v_mfma_f32_16x16x32_bf16 v[32:35], v[218:221], v[186:189], v[32:35]
	v_mfma_f32_16x16x32_bf16 v[20:23], v[210:213], v[194:197], v[20:23]
	v_mfma_f32_16x16x32_bf16 v[16:19], v[218:221], v[194:197], v[16:19]
	v_mfma_f32_16x16x32_bf16 v[4:7], v[210:213], v[202:205], v[4:7]
	v_mfma_f32_16x16x32_bf16 v[0:3], v[218:221], v[202:205], v[0:3]
	s_setprio 0
	s_add_i32 s53, s53, 2
	s_add_u32 s51, s51, 0x100
	s_addc_u32 s52, s52, 0
	s_cmp_gt_u32 s53, 41
	s_mov_b64 s[18:19], s[20:21]
	s_barrier
	s_cbranch_scc0 .LBB0_1503
	v_lshl_add_u32 v146, s50, 8, v148
	v_ashrrev_i32_e32 v147, 31, v146
	v_lshl_or_b32 v144, s49, 8, v150
	v_lshlrev_b64 v[156:157], 12, v[146:147]
	v_lshl_add_u64 v[156:157], s[38:39], 0, v[156:157]
	v_ashrrev_i32_e32 v145, 31, v144
	v_lshl_add_u64 v[168:169], v[144:145], 2, v[156:157]
	global_load_dwordx4 v[156:159], v[168:169], off
	global_load_dwordx4 v[160:163], v[168:169], off offset:16
	v_lshlrev_b64 v[164:165], 11, v[146:147]
	v_lshl_add_u64 v[164:165], s[40:41], 0, v[164:165]
	v_lshl_add_u64 v[170:171], v[144:145], 1, v[164:165]
	v_xor_b32_e32 v155, 32, v154
	s_waitcnt vmcnt(0)
	v_pk_fma_f32 v[126:127], v[126:127], 0.5, v[158:159] op_sel_hi:[1,0,1]
	v_pk_fma_f32 v[124:125], v[124:125], 0.5, v[156:157] op_sel_hi:[1,0,1]
	v_pk_fma_f32 v[158:159], v[122:123], 0.5, v[162:163] op_sel_hi:[1,0,1]
	v_pk_fma_f32 v[156:157], v[120:121], 0.5, v[160:161] op_sel_hi:[1,0,1]
	global_store_dwordx4 v[168:169], v[124:127], off
	global_store_dwordx4 v[168:169], v[156:159], off offset:16
	v_cvt_pk_bf16_f32 v120, v124, v125
	v_cvt_pk_bf16_f32 v121, v126, v127
	v_cvt_pk_bf16_f32 v122, v156, v157
	v_cvt_pk_bf16_f32 v123, v158, v159
	global_load_dwordx4 v[160:163], v[168:169], off offset:512
	global_load_dwordx4 v[164:167], v[168:169], off offset:528
	v_mul_f32_e32 v122, v125, v125
	v_mul_f32_e32 v123, v127, v127
	v_mul_f32_e32 v125, v157, v157
	v_fmac_f32_e32 v122, v124, v124
	v_fmac_f32_e32 v123, v126, v126
	v_mul_f32_e32 v127, v159, v159
	v_fmac_f32_e32 v125, v156, v156
	v_add_f32_e32 v122, v122, v123
	v_fmac_f32_e32 v127, v158, v158
	v_add_f32_e32 v122, v125, v122
	v_add_f32_e32 v126, v127, v122
	v_and_b32_e32 v121, 64, v154
	v_xor_b32_e32 v120, 16, v154
	v_add_u32_e32 v121, 64, v121
	v_cmp_lt_i32_e32 vcc, v120, v121
	s_waitcnt vmcnt(0)
	v_pk_fma_f32 v[118:119], v[118:119], 0.5, v[162:163] op_sel_hi:[1,0,1]
	v_pk_fma_f32 v[116:117], v[116:117], 0.5, v[160:161] op_sel_hi:[1,0,1]
	v_pk_fma_f32 v[122:123], v[112:113], 0.5, v[164:165] op_sel_hi:[1,0,1]
	v_mul_f32_e32 v112, v117, v117
	v_mul_f32_e32 v113, v119, v119
	v_pk_fma_f32 v[124:125], v[114:115], 0.5, v[166:167] op_sel_hi:[1,0,1]
	v_mul_f32_e32 v114, v123, v123
	v_fmac_f32_e32 v112, v116, v116
	v_fmac_f32_e32 v113, v118, v118
	v_mul_f32_e32 v115, v125, v125
	v_fmac_f32_e32 v114, v122, v122
	v_add_f32_e32 v112, v112, v113
	v_fmac_f32_e32 v115, v124, v124
	v_add_f32_e32 v112, v114, v112
	v_cndmask_b32_e32 v120, v154, v120, vcc
	v_add_f32_e32 v112, v115, v112
	v_lshlrev_b32_e32 v120, 2, v120
	v_add_f32_e32 v112, v126, v112
	ds_bpermute_b32 v113, v120, v112
	v_cmp_lt_i32_e32 vcc, v155, v121
	global_store_dwordx4 v[168:169], v[116:119], off offset:512
	global_store_dwordx4 v[168:169], v[122:125], off offset:528
	v_cndmask_b32_e32 v114, v154, v155, vcc
	v_lshlrev_b32_e32 v114, 2, v114
	s_waitcnt lgkmcnt(0)
	v_add_f32_e32 v112, v112, v113
	ds_bpermute_b32 v113, v114, v112
	v_cvt_pk_bf16_f32 v116, v116, v117
	v_cvt_pk_bf16_f32 v117, v118, v119
	v_cvt_pk_bf16_f32 v118, v122, v123
	v_cvt_pk_bf16_f32 v119, v124, v125
	s_and_saveexec_b64 s[18:19], s[4:5]
	s_cbranch_execz .LBB0_1506
	v_lshl_add_u64 v[116:117], v[146:147], 2, s[12:13]
	s_waitcnt lgkmcnt(0)
	v_add_f32_e32 v112, v112, v113
	global_atomic_add_f32 v[116:117], v112, off
.LBB0_1506:
	s_or_b64 exec, exec, s[18:19]
	v_or_b32_e32 v112, 16, v146
	s_waitcnt lgkmcnt(0)
	v_ashrrev_i32_e32 v113, 31, v112
	v_lshlrev_b64 v[116:117], 12, v[112:113]
	v_lshl_add_u64 v[116:117], s[38:39], 0, v[116:117]
	v_lshl_add_u64 v[126:127], v[144:145], 2, v[116:117]
	global_load_dwordx4 v[116:119], v[126:127], off
	global_load_dwordx4 v[122:125], v[126:127], off offset:16
	v_lshlrev_b64 v[156:157], 11, v[112:113]
	v_lshl_add_u64 v[156:157], s[40:41], 0, v[156:157]
	v_lshl_add_u64 v[156:157], v[144:145], 1, v[156:157]
	s_waitcnt vmcnt(1)
	v_pk_fma_f32 v[110:111], v[110:111], 0.5, v[118:119] op_sel_hi:[1,0,1]
	v_pk_fma_f32 v[108:109], v[108:109], 0.5, v[116:117] op_sel_hi:[1,0,1]
	s_waitcnt vmcnt(0)
	v_pk_fma_f32 v[106:107], v[106:107], 0.5, v[124:125] op_sel_hi:[1,0,1]
	v_pk_fma_f32 v[104:105], v[104:105], 0.5, v[122:123] op_sel_hi:[1,0,1]
	global_store_dwordx4 v[126:127], v[108:111], off
	global_store_dwordx4 v[126:127], v[104:107], off offset:16
	v_cvt_pk_bf16_f32 v116, v108, v109
	v_cvt_pk_bf16_f32 v117, v110, v111
	v_cvt_pk_bf16_f32 v118, v104, v105
	v_cvt_pk_bf16_f32 v119, v106, v107
	global_load_dwordx4 v[116:119], v[126:127], off offset:512
	s_nop 0
	global_load_dwordx4 v[122:125], v[126:127], off offset:528
	v_mul_f32_e32 v109, v109, v109
	v_mul_f32_e32 v111, v111, v111
	v_mul_f32_e32 v105, v105, v105
	v_fmac_f32_e32 v109, v108, v108
	v_fmac_f32_e32 v111, v110, v110
	v_mul_f32_e32 v107, v107, v107
	v_fmac_f32_e32 v105, v104, v104
	v_add_f32_e32 v104, v109, v111
	v_fmac_f32_e32 v107, v106, v106
	v_add_f32_e32 v104, v105, v104
	v_add_f32_e32 v108, v107, v104
	s_waitcnt vmcnt(1)
	v_pk_fma_f32 v[102:103], v[102:103], 0.5, v[118:119] op_sel_hi:[1,0,1]
	v_pk_fma_f32 v[100:101], v[100:101], 0.5, v[116:117] op_sel_hi:[1,0,1]
	s_waitcnt vmcnt(0)
	v_pk_fma_f32 v[104:105], v[96:97], 0.5, v[122:123] op_sel_hi:[1,0,1]
	v_mul_f32_e32 v96, v101, v101
	v_mul_f32_e32 v97, v103, v103
	v_pk_fma_f32 v[106:107], v[98:99], 0.5, v[124:125] op_sel_hi:[1,0,1]
	v_mul_f32_e32 v98, v105, v105
	v_fmac_f32_e32 v96, v100, v100
	v_fmac_f32_e32 v97, v102, v102
	v_mul_f32_e32 v99, v107, v107
	v_fmac_f32_e32 v98, v104, v104
	v_add_f32_e32 v96, v96, v97
	v_add_f32_e32 v96, v98, v96
	v_fmac_f32_e32 v99, v106, v106
	v_add_f32_e32 v96, v99, v96
	v_add_f32_e32 v96, v108, v96
	ds_bpermute_b32 v97, v120, v96
	global_store_dwordx4 v[126:127], v[100:103], off offset:512
	global_store_dwordx4 v[126:127], v[104:107], off offset:528
	v_cvt_pk_bf16_f32 v98, v100, v101
	v_cvt_pk_bf16_f32 v99, v102, v103
	s_waitcnt lgkmcnt(0)
	v_add_f32_e32 v96, v96, v97
	ds_bpermute_b32 v97, v114, v96
	v_cvt_pk_bf16_f32 v100, v104, v105
	v_cvt_pk_bf16_f32 v101, v106, v107
	s_and_saveexec_b64 s[18:19], s[4:5]
	s_cbranch_execz .LBB0_1508
	v_lshl_add_u64 v[98:99], v[112:113], 2, s[12:13]
	s_waitcnt lgkmcnt(0)
	v_add_f32_e32 v96, v96, v97
	global_atomic_add_f32 v[98:99], v96, off
.LBB0_1508:
	s_or_b64 exec, exec, s[18:19]
	v_or_b32_e32 v96, 32, v146
	s_waitcnt lgkmcnt(0)
	v_ashrrev_i32_e32 v97, 31, v96
	v_lshlrev_b64 v[98:99], 12, v[96:97]
	v_lshl_add_u64 v[98:99], s[38:39], 0, v[98:99]
	v_lshl_add_u64 v[106:107], v[144:145], 2, v[98:99]
	global_load_dwordx4 v[98:101], v[106:107], off
	global_load_dwordx4 v[102:105], v[106:107], off offset:16
	v_lshlrev_b64 v[108:109], 11, v[96:97]
	v_lshl_add_u64 v[108:109], s[40:41], 0, v[108:109]
	v_lshl_add_u64 v[108:109], v[144:145], 1, v[108:109]
	s_waitcnt vmcnt(1)
	v_pk_fma_f32 v[94:95], v[94:95], 0.5, v[100:101] op_sel_hi:[1,0,1]
	v_pk_fma_f32 v[92:93], v[92:93], 0.5, v[98:99] op_sel_hi:[1,0,1]
	s_waitcnt vmcnt(0)
	v_pk_fma_f32 v[90:91], v[90:91], 0.5, v[104:105] op_sel_hi:[1,0,1]
	v_pk_fma_f32 v[88:89], v[88:89], 0.5, v[102:103] op_sel_hi:[1,0,1]
	global_store_dwordx4 v[106:107], v[92:95], off
	global_store_dwordx4 v[106:107], v[88:91], off offset:16
	v_cvt_pk_bf16_f32 v98, v92, v93
	v_cvt_pk_bf16_f32 v99, v94, v95
	v_cvt_pk_bf16_f32 v100, v88, v89
	v_cvt_pk_bf16_f32 v101, v90, v91
	global_load_dwordx4 v[98:101], v[106:107], off offset:512
	s_nop 0
	global_load_dwordx4 v[102:105], v[106:107], off offset:528
	v_mul_f32_e32 v93, v93, v93
	v_mul_f32_e32 v95, v95, v95
	v_mul_f32_e32 v89, v89, v89
	v_fmac_f32_e32 v93, v92, v92
	v_fmac_f32_e32 v95, v94, v94
	v_mul_f32_e32 v91, v91, v91
	v_fmac_f32_e32 v89, v88, v88
	v_add_f32_e32 v88, v93, v95
	v_fmac_f32_e32 v91, v90, v90
	v_add_f32_e32 v88, v89, v88
	v_add_f32_e32 v92, v91, v88
	s_waitcnt vmcnt(1)
	v_pk_fma_f32 v[86:87], v[86:87], 0.5, v[100:101] op_sel_hi:[1,0,1]
	v_pk_fma_f32 v[84:85], v[84:85], 0.5, v[98:99] op_sel_hi:[1,0,1]
	s_waitcnt vmcnt(0)
	v_pk_fma_f32 v[88:89], v[80:81], 0.5, v[102:103] op_sel_hi:[1,0,1]
	v_mul_f32_e32 v80, v85, v85
	v_mul_f32_e32 v81, v87, v87
	v_pk_fma_f32 v[90:91], v[82:83], 0.5, v[104:105] op_sel_hi:[1,0,1]
	v_mul_f32_e32 v82, v89, v89
	v_fmac_f32_e32 v80, v84, v84
	v_fmac_f32_e32 v81, v86, v86
	v_mul_f32_e32 v83, v91, v91
	v_fmac_f32_e32 v82, v88, v88
	v_add_f32_e32 v80, v80, v81
	v_add_f32_e32 v80, v82, v80
	v_fmac_f32_e32 v83, v90, v90
	v_add_f32_e32 v80, v83, v80
	v_add_f32_e32 v80, v92, v80
	ds_bpermute_b32 v81, v120, v80
	global_store_dwordx4 v[106:107], v[84:87], off offset:512
	global_store_dwordx4 v[106:107], v[88:91], off offset:528
	v_cvt_pk_bf16_f32 v82, v84, v85
	v_cvt_pk_bf16_f32 v83, v86, v87
	s_waitcnt lgkmcnt(0)
	v_add_f32_e32 v80, v80, v81
	ds_bpermute_b32 v81, v114, v80
	v_cvt_pk_bf16_f32 v84, v88, v89
	v_cvt_pk_bf16_f32 v85, v90, v91
	s_and_saveexec_b64 s[18:19], s[4:5]
	s_cbranch_execz .LBB0_1510
	v_lshl_add_u64 v[82:83], v[96:97], 2, s[12:13]
	s_waitcnt lgkmcnt(0)
	v_add_f32_e32 v80, v80, v81
	global_atomic_add_f32 v[82:83], v80, off
.LBB0_1510:
	s_or_b64 exec, exec, s[18:19]
	v_or_b32_e32 v80, 48, v146
	s_waitcnt lgkmcnt(0)
	v_ashrrev_i32_e32 v81, 31, v80
	v_lshlrev_b64 v[82:83], 12, v[80:81]
	v_lshl_add_u64 v[82:83], s[38:39], 0, v[82:83]
	v_lshl_add_u64 v[90:91], v[144:145], 2, v[82:83]
	global_load_dwordx4 v[82:85], v[90:91], off
	global_load_dwordx4 v[86:89], v[90:91], off offset:16
	v_lshlrev_b64 v[92:93], 11, v[80:81]
	v_lshl_add_u64 v[92:93], s[40:41], 0, v[92:93]
	v_lshl_add_u64 v[92:93], v[144:145], 1, v[92:93]
	s_waitcnt vmcnt(1)
	v_pk_fma_f32 v[78:79], v[78:79], 0.5, v[84:85] op_sel_hi:[1,0,1]
	v_pk_fma_f32 v[76:77], v[76:77], 0.5, v[82:83] op_sel_hi:[1,0,1]
	s_waitcnt vmcnt(0)
	v_pk_fma_f32 v[74:75], v[74:75], 0.5, v[88:89] op_sel_hi:[1,0,1]
	v_pk_fma_f32 v[72:73], v[72:73], 0.5, v[86:87] op_sel_hi:[1,0,1]
	global_store_dwordx4 v[90:91], v[76:79], off
	global_store_dwordx4 v[90:91], v[72:75], off offset:16
	v_cvt_pk_bf16_f32 v82, v76, v77
	v_cvt_pk_bf16_f32 v83, v78, v79
	v_cvt_pk_bf16_f32 v84, v72, v73
	v_cvt_pk_bf16_f32 v85, v74, v75
	global_load_dwordx4 v[82:85], v[90:91], off offset:512
	s_nop 0
	global_load_dwordx4 v[86:89], v[90:91], off offset:528
	v_mul_f32_e32 v77, v77, v77
	v_mul_f32_e32 v79, v79, v79
	v_mul_f32_e32 v73, v73, v73
	v_fmac_f32_e32 v77, v76, v76
	v_fmac_f32_e32 v79, v78, v78
	v_mul_f32_e32 v75, v75, v75
	v_fmac_f32_e32 v73, v72, v72
	v_add_f32_e32 v72, v77, v79
	v_fmac_f32_e32 v75, v74, v74
	v_add_f32_e32 v72, v73, v72
	v_add_f32_e32 v76, v75, v72
	s_waitcnt vmcnt(1)
	v_pk_fma_f32 v[70:71], v[70:71], 0.5, v[84:85] op_sel_hi:[1,0,1]
	v_pk_fma_f32 v[68:69], v[68:69], 0.5, v[82:83] op_sel_hi:[1,0,1]
	s_waitcnt vmcnt(0)
	v_pk_fma_f32 v[72:73], v[64:65], 0.5, v[86:87] op_sel_hi:[1,0,1]
	v_mul_f32_e32 v64, v69, v69
	v_mul_f32_e32 v65, v71, v71
	v_pk_fma_f32 v[74:75], v[66:67], 0.5, v[88:89] op_sel_hi:[1,0,1]
	v_mul_f32_e32 v66, v73, v73
	v_fmac_f32_e32 v64, v68, v68
	v_fmac_f32_e32 v65, v70, v70
	v_mul_f32_e32 v67, v75, v75
	v_fmac_f32_e32 v66, v72, v72
	v_add_f32_e32 v64, v64, v65
	v_add_f32_e32 v64, v66, v64
	v_fmac_f32_e32 v67, v74, v74
	v_add_f32_e32 v64, v67, v64
	v_add_f32_e32 v64, v76, v64
	ds_bpermute_b32 v65, v120, v64
	global_store_dwordx4 v[90:91], v[68:71], off offset:512
	global_store_dwordx4 v[90:91], v[72:75], off offset:528
	v_cvt_pk_bf16_f32 v66, v68, v69
	v_cvt_pk_bf16_f32 v67, v70, v71
	s_waitcnt lgkmcnt(0)
	v_add_f32_e32 v64, v64, v65
	ds_bpermute_b32 v65, v114, v64
	v_cvt_pk_bf16_f32 v68, v72, v73
	v_cvt_pk_bf16_f32 v69, v74, v75
	s_and_saveexec_b64 s[18:19], s[4:5]
	s_cbranch_execz .LBB0_1512
	v_lshl_add_u64 v[66:67], v[80:81], 2, s[12:13]
	s_waitcnt lgkmcnt(0)
	v_add_f32_e32 v64, v64, v65
	global_atomic_add_f32 v[66:67], v64, off
.LBB0_1512:
	s_or_b64 exec, exec, s[18:19]
	v_add_u32_e32 v64, 0x80, v146
	s_waitcnt lgkmcnt(0)
	v_ashrrev_i32_e32 v65, 31, v64
	v_lshlrev_b64 v[66:67], 12, v[64:65]
	v_lshl_add_u64 v[66:67], s[38:39], 0, v[66:67]
	v_lshl_add_u64 v[74:75], v[144:145], 2, v[66:67]
	global_load_dwordx4 v[66:69], v[74:75], off
	global_load_dwordx4 v[70:73], v[74:75], off offset:16
	v_lshlrev_b64 v[76:77], 11, v[64:65]
	v_lshl_add_u64 v[76:77], s[40:41], 0, v[76:77]
	v_lshl_add_u64 v[76:77], v[144:145], 1, v[76:77]
	s_waitcnt vmcnt(1)
	v_pk_fma_f32 v[62:63], v[62:63], 0.5, v[68:69] op_sel_hi:[1,0,1]
	v_pk_fma_f32 v[60:61], v[60:61], 0.5, v[66:67] op_sel_hi:[1,0,1]
	s_waitcnt vmcnt(0)
	v_pk_fma_f32 v[58:59], v[58:59], 0.5, v[72:73] op_sel_hi:[1,0,1]
	v_pk_fma_f32 v[56:57], v[56:57], 0.5, v[70:71] op_sel_hi:[1,0,1]
	global_store_dwordx4 v[74:75], v[60:63], off
	global_store_dwordx4 v[74:75], v[56:59], off offset:16
	v_cvt_pk_bf16_f32 v66, v60, v61
	v_cvt_pk_bf16_f32 v67, v62, v63
	v_cvt_pk_bf16_f32 v68, v56, v57
	v_cvt_pk_bf16_f32 v69, v58, v59
	global_load_dwordx4 v[66:69], v[74:75], off offset:512
	s_nop 0
	global_load_dwordx4 v[70:73], v[74:75], off offset:528
	v_mul_f32_e32 v61, v61, v61
	v_mul_f32_e32 v63, v63, v63
	v_mul_f32_e32 v57, v57, v57
	v_fmac_f32_e32 v61, v60, v60
	v_fmac_f32_e32 v63, v62, v62
	v_mul_f32_e32 v59, v59, v59
	v_fmac_f32_e32 v57, v56, v56
	v_add_f32_e32 v56, v61, v63
	v_fmac_f32_e32 v59, v58, v58
	v_add_f32_e32 v56, v57, v56
	v_add_f32_e32 v60, v59, v56
	s_waitcnt vmcnt(1)
	v_pk_fma_f32 v[54:55], v[54:55], 0.5, v[68:69] op_sel_hi:[1,0,1]
	v_pk_fma_f32 v[52:53], v[52:53], 0.5, v[66:67] op_sel_hi:[1,0,1]
	s_waitcnt vmcnt(0)
	v_pk_fma_f32 v[56:57], v[48:49], 0.5, v[70:71] op_sel_hi:[1,0,1]
	v_mul_f32_e32 v48, v53, v53
	v_mul_f32_e32 v49, v55, v55
	v_pk_fma_f32 v[58:59], v[50:51], 0.5, v[72:73] op_sel_hi:[1,0,1]
	v_mul_f32_e32 v50, v57, v57
	v_fmac_f32_e32 v48, v52, v52
	v_fmac_f32_e32 v49, v54, v54
	v_mul_f32_e32 v51, v59, v59
	v_fmac_f32_e32 v50, v56, v56
	v_add_f32_e32 v48, v48, v49
	v_add_f32_e32 v48, v50, v48
	v_fmac_f32_e32 v51, v58, v58
	v_add_f32_e32 v48, v51, v48
	v_add_f32_e32 v48, v60, v48
	ds_bpermute_b32 v49, v120, v48
	global_store_dwordx4 v[74:75], v[52:55], off offset:512
	global_store_dwordx4 v[74:75], v[56:59], off offset:528
	v_cvt_pk_bf16_f32 v50, v52, v53
	v_cvt_pk_bf16_f32 v51, v54, v55
	s_waitcnt lgkmcnt(0)
	v_add_f32_e32 v48, v48, v49
	ds_bpermute_b32 v49, v114, v48
	v_cvt_pk_bf16_f32 v52, v56, v57
	v_cvt_pk_bf16_f32 v53, v58, v59
	s_and_saveexec_b64 s[18:19], s[4:5]
	s_cbranch_execz .LBB0_1514
	v_lshl_add_u64 v[50:51], v[64:65], 2, s[12:13]
	s_waitcnt lgkmcnt(0)
	v_add_f32_e32 v48, v48, v49
	global_atomic_add_f32 v[50:51], v48, off
.LBB0_1514:
	s_or_b64 exec, exec, s[18:19]
	v_add_u32_e32 v48, 0x90, v146
	s_waitcnt lgkmcnt(0)
	v_ashrrev_i32_e32 v49, 31, v48
	v_lshlrev_b64 v[50:51], 12, v[48:49]
	v_lshl_add_u64 v[50:51], s[38:39], 0, v[50:51]
	v_lshl_add_u64 v[58:59], v[144:145], 2, v[50:51]
	global_load_dwordx4 v[50:53], v[58:59], off
	global_load_dwordx4 v[54:57], v[58:59], off offset:16
	v_lshlrev_b64 v[60:61], 11, v[48:49]
	v_lshl_add_u64 v[60:61], s[40:41], 0, v[60:61]
	v_lshl_add_u64 v[60:61], v[144:145], 1, v[60:61]
	s_waitcnt vmcnt(1)
	v_pk_fma_f32 v[46:47], v[46:47], 0.5, v[52:53] op_sel_hi:[1,0,1]
	v_pk_fma_f32 v[44:45], v[44:45], 0.5, v[50:51] op_sel_hi:[1,0,1]
	s_waitcnt vmcnt(0)
	v_pk_fma_f32 v[42:43], v[42:43], 0.5, v[56:57] op_sel_hi:[1,0,1]
	v_pk_fma_f32 v[40:41], v[40:41], 0.5, v[54:55] op_sel_hi:[1,0,1]
	global_store_dwordx4 v[58:59], v[44:47], off
	global_store_dwordx4 v[58:59], v[40:43], off offset:16
	v_cvt_pk_bf16_f32 v50, v44, v45
	v_cvt_pk_bf16_f32 v51, v46, v47
	v_cvt_pk_bf16_f32 v52, v40, v41
	v_cvt_pk_bf16_f32 v53, v42, v43
	global_load_dwordx4 v[50:53], v[58:59], off offset:512
	s_nop 0
	global_load_dwordx4 v[54:57], v[58:59], off offset:528
	v_mul_f32_e32 v45, v45, v45
	v_mul_f32_e32 v47, v47, v47
	v_mul_f32_e32 v41, v41, v41
	v_fmac_f32_e32 v45, v44, v44
	v_fmac_f32_e32 v47, v46, v46
	v_mul_f32_e32 v43, v43, v43
	v_fmac_f32_e32 v41, v40, v40
	v_add_f32_e32 v40, v45, v47
	v_fmac_f32_e32 v43, v42, v42
	v_add_f32_e32 v40, v41, v40
	v_add_f32_e32 v44, v43, v40
	s_waitcnt vmcnt(1)
	v_pk_fma_f32 v[38:39], v[38:39], 0.5, v[52:53] op_sel_hi:[1,0,1]
	v_pk_fma_f32 v[36:37], v[36:37], 0.5, v[50:51] op_sel_hi:[1,0,1]
	s_waitcnt vmcnt(0)
	v_pk_fma_f32 v[40:41], v[32:33], 0.5, v[54:55] op_sel_hi:[1,0,1]
	v_mul_f32_e32 v32, v37, v37
	v_mul_f32_e32 v33, v39, v39
	v_pk_fma_f32 v[42:43], v[34:35], 0.5, v[56:57] op_sel_hi:[1,0,1]
	v_mul_f32_e32 v34, v41, v41
	v_fmac_f32_e32 v32, v36, v36
	v_fmac_f32_e32 v33, v38, v38
	v_mul_f32_e32 v35, v43, v43
	v_fmac_f32_e32 v34, v40, v40
	v_add_f32_e32 v32, v32, v33
	v_add_f32_e32 v32, v34, v32
	v_fmac_f32_e32 v35, v42, v42
	v_add_f32_e32 v32, v35, v32
	v_add_f32_e32 v32, v44, v32
	ds_bpermute_b32 v33, v120, v32
	global_store_dwordx4 v[58:59], v[36:39], off offset:512
	global_store_dwordx4 v[58:59], v[40:43], off offset:528
	v_cvt_pk_bf16_f32 v34, v36, v37
	v_cvt_pk_bf16_f32 v35, v38, v39
	s_waitcnt lgkmcnt(0)
	v_add_f32_e32 v32, v32, v33
	ds_bpermute_b32 v33, v114, v32
	v_cvt_pk_bf16_f32 v36, v40, v41
	v_cvt_pk_bf16_f32 v37, v42, v43
	s_and_saveexec_b64 s[18:19], s[4:5]
	s_cbranch_execz .LBB0_1516
	v_lshl_add_u64 v[34:35], v[48:49], 2, s[12:13]
	s_waitcnt lgkmcnt(0)
	v_add_f32_e32 v32, v32, v33
	global_atomic_add_f32 v[34:35], v32, off
.LBB0_1516:
	s_or_b64 exec, exec, s[18:19]
	v_add_u32_e32 v32, 0xa0, v146
	s_waitcnt lgkmcnt(0)
	v_ashrrev_i32_e32 v33, 31, v32
	v_lshlrev_b64 v[34:35], 12, v[32:33]
	v_lshl_add_u64 v[34:35], s[38:39], 0, v[34:35]
	v_lshl_add_u64 v[42:43], v[144:145], 2, v[34:35]
	global_load_dwordx4 v[34:37], v[42:43], off
	global_load_dwordx4 v[38:41], v[42:43], off offset:16
	v_lshlrev_b64 v[44:45], 11, v[32:33]
	v_lshl_add_u64 v[44:45], s[40:41], 0, v[44:45]
	v_lshl_add_u64 v[44:45], v[144:145], 1, v[44:45]
	s_waitcnt vmcnt(1)
	v_pk_fma_f32 v[30:31], v[30:31], 0.5, v[36:37] op_sel_hi:[1,0,1]
	v_pk_fma_f32 v[28:29], v[28:29], 0.5, v[34:35] op_sel_hi:[1,0,1]
	s_waitcnt vmcnt(0)
	v_pk_fma_f32 v[26:27], v[26:27], 0.5, v[40:41] op_sel_hi:[1,0,1]
	v_pk_fma_f32 v[24:25], v[24:25], 0.5, v[38:39] op_sel_hi:[1,0,1]
	global_store_dwordx4 v[42:43], v[28:31], off
	global_store_dwordx4 v[42:43], v[24:27], off offset:16
	v_cvt_pk_bf16_f32 v34, v28, v29
	v_cvt_pk_bf16_f32 v35, v30, v31
	v_cvt_pk_bf16_f32 v36, v24, v25
	v_cvt_pk_bf16_f32 v37, v26, v27
	global_load_dwordx4 v[34:37], v[42:43], off offset:512
	s_nop 0
	global_load_dwordx4 v[38:41], v[42:43], off offset:528
	v_mul_f32_e32 v29, v29, v29
	v_mul_f32_e32 v31, v31, v31
	v_mul_f32_e32 v25, v25, v25
	v_fmac_f32_e32 v29, v28, v28
	v_fmac_f32_e32 v31, v30, v30
	v_mul_f32_e32 v27, v27, v27
	v_fmac_f32_e32 v25, v24, v24
	v_add_f32_e32 v24, v29, v31
	v_fmac_f32_e32 v27, v26, v26
	v_add_f32_e32 v24, v25, v24
	v_add_f32_e32 v28, v27, v24
	s_waitcnt vmcnt(1)
	v_pk_fma_f32 v[22:23], v[22:23], 0.5, v[36:37] op_sel_hi:[1,0,1]
	v_pk_fma_f32 v[20:21], v[20:21], 0.5, v[34:35] op_sel_hi:[1,0,1]
	s_waitcnt vmcnt(0)
	v_pk_fma_f32 v[24:25], v[16:17], 0.5, v[38:39] op_sel_hi:[1,0,1]
	v_mul_f32_e32 v16, v21, v21
	v_mul_f32_e32 v17, v23, v23
	v_pk_fma_f32 v[26:27], v[18:19], 0.5, v[40:41] op_sel_hi:[1,0,1]
	v_mul_f32_e32 v18, v25, v25
	v_fmac_f32_e32 v16, v20, v20
	v_fmac_f32_e32 v17, v22, v22
	v_mul_f32_e32 v19, v27, v27
	v_fmac_f32_e32 v18, v24, v24
	v_add_f32_e32 v16, v16, v17
	v_add_f32_e32 v16, v18, v16
	v_fmac_f32_e32 v19, v26, v26
	v_add_f32_e32 v16, v19, v16
	v_add_f32_e32 v16, v28, v16
	ds_bpermute_b32 v17, v120, v16
	global_store_dwordx4 v[42:43], v[20:23], off offset:512
	global_store_dwordx4 v[42:43], v[24:27], off offset:528
	v_cvt_pk_bf16_f32 v18, v20, v21
	v_cvt_pk_bf16_f32 v19, v22, v23
	s_waitcnt lgkmcnt(0)
	v_add_f32_e32 v16, v16, v17
	ds_bpermute_b32 v17, v114, v16
	v_cvt_pk_bf16_f32 v20, v24, v25
	v_cvt_pk_bf16_f32 v21, v26, v27
	s_and_saveexec_b64 s[18:19], s[4:5]
	s_cbranch_execz .LBB0_1518
	v_lshl_add_u64 v[18:19], v[32:33], 2, s[12:13]
	s_waitcnt lgkmcnt(0)
	v_add_f32_e32 v16, v16, v17
	global_atomic_add_f32 v[18:19], v16, off
.LBB0_1518:
	s_or_b64 exec, exec, s[18:19]
	v_add_u32_e32 v16, 0xb0, v146
	s_waitcnt lgkmcnt(0)
	v_ashrrev_i32_e32 v17, 31, v16
	v_lshlrev_b64 v[18:19], 12, v[16:17]
	v_lshl_add_u64 v[18:19], s[38:39], 0, v[18:19]
	v_lshl_add_u64 v[26:27], v[144:145], 2, v[18:19]
	global_load_dwordx4 v[18:21], v[26:27], off
	global_load_dwordx4 v[22:25], v[26:27], off offset:16
	v_lshlrev_b64 v[28:29], 11, v[16:17]
	v_lshl_add_u64 v[28:29], s[40:41], 0, v[28:29]
	v_lshl_add_u64 v[28:29], v[144:145], 1, v[28:29]
	s_waitcnt vmcnt(1)
	v_pk_fma_f32 v[14:15], v[14:15], 0.5, v[20:21] op_sel_hi:[1,0,1]
	v_pk_fma_f32 v[12:13], v[12:13], 0.5, v[18:19] op_sel_hi:[1,0,1]
	s_waitcnt vmcnt(0)
	v_pk_fma_f32 v[10:11], v[10:11], 0.5, v[24:25] op_sel_hi:[1,0,1]
	v_pk_fma_f32 v[8:9], v[8:9], 0.5, v[22:23] op_sel_hi:[1,0,1]
	global_store_dwordx4 v[26:27], v[12:15], off
	global_store_dwordx4 v[26:27], v[8:11], off offset:16
	v_cvt_pk_bf16_f32 v18, v12, v13
	v_cvt_pk_bf16_f32 v19, v14, v15
	v_cvt_pk_bf16_f32 v20, v8, v9
	v_cvt_pk_bf16_f32 v21, v10, v11
	global_load_dwordx4 v[18:21], v[26:27], off offset:512
	s_nop 0
	global_load_dwordx4 v[22:25], v[26:27], off offset:528
	v_mul_f32_e32 v13, v13, v13
	v_mul_f32_e32 v15, v15, v15
	v_mul_f32_e32 v9, v9, v9
	v_fmac_f32_e32 v13, v12, v12
	v_fmac_f32_e32 v15, v14, v14
	v_mul_f32_e32 v11, v11, v11
	v_fmac_f32_e32 v9, v8, v8
	v_add_f32_e32 v8, v13, v15
	v_fmac_f32_e32 v11, v10, v10
	v_add_f32_e32 v8, v9, v8
	v_add_f32_e32 v12, v11, v8
	s_waitcnt vmcnt(1)
	v_pk_fma_f32 v[6:7], v[6:7], 0.5, v[20:21] op_sel_hi:[1,0,1]
	v_pk_fma_f32 v[4:5], v[4:5], 0.5, v[18:19] op_sel_hi:[1,0,1]
	s_waitcnt vmcnt(0)
	v_pk_fma_f32 v[8:9], v[0:1], 0.5, v[22:23] op_sel_hi:[1,0,1]
	v_mul_f32_e32 v0, v5, v5
	v_mul_f32_e32 v1, v7, v7
	v_pk_fma_f32 v[10:11], v[2:3], 0.5, v[24:25] op_sel_hi:[1,0,1]
	v_mul_f32_e32 v2, v9, v9
	v_fmac_f32_e32 v0, v4, v4
	v_fmac_f32_e32 v1, v6, v6
	v_mul_f32_e32 v3, v11, v11
	v_fmac_f32_e32 v2, v8, v8
	v_add_f32_e32 v0, v0, v1
	v_add_f32_e32 v0, v2, v0
	v_fmac_f32_e32 v3, v10, v10
	v_add_f32_e32 v0, v3, v0
	v_add_f32_e32 v0, v12, v0
	ds_bpermute_b32 v1, v120, v0
	global_store_dwordx4 v[26:27], v[4:7], off offset:512
	global_store_dwordx4 v[26:27], v[8:11], off offset:528
	v_cvt_pk_bf16_f32 v2, v4, v5
	v_cvt_pk_bf16_f32 v3, v6, v7
	s_waitcnt lgkmcnt(0)
	v_add_f32_e32 v0, v0, v1
	ds_bpermute_b32 v1, v114, v0
	v_cvt_pk_bf16_f32 v4, v8, v9
	v_cvt_pk_bf16_f32 v5, v10, v11
	s_and_saveexec_b64 s[18:19], s[4:5]
	s_cbranch_execz .LBB0_1491
	v_lshl_add_u64 v[2:3], v[16:17], 2, s[12:13]
	s_waitcnt lgkmcnt(0)
	v_add_f32_e32 v0, v0, v1
	global_atomic_add_f32 v[2:3], v0, off
	s_branch .LBB0_1491

.LBB0_1523:
	v_and_b32_e32 v160, 15, v174
	v_bfe_u32 v161, v174, 4, 2
	v_lshrrev_b32_e32 v162, 6, v174
	v_and_b32_e32 v136, 63, v174
	v_readfirstlane_b32 s80, v162
	s_lshr_b32 s81, s33, 8
	s_lshr_b32 s82, s33, 3
	s_and_b32 s82, s82, 31
	s_mul_i32 s83, s80, 704
	v_lshlrev_b32_e32 v164, 4, v161
	v_mov_b32_e32 v167, 0
	s_lshl_b32 s84, s82, 5
	v_add_u32_e32 v165, s84, v160
	v_mul_u32_u24_e32 v166, 0x1600, v165
	v_add3_u32 v166, v166, v164, s83
	s_add_u32 s86, s74, 0x3c80000
	s_addc_u32 s87, s75, 0
	s_mov_b32 s88, 0x16000
	s_mov_b32 s89, 0
	v_lshl_add_u64 v[152:153], s[86:87], 0, v[166:167]
	v_lshl_add_u64 v[154:155], v[152:153], 0, s[88:89]
	s_lshl_b32 s84, s81, 5
	v_add_u32_e32 v165, s84, v160
	v_mul_u32_u24_e32 v166, 0x1600, v165
	v_add3_u32 v166, v166, v164, s83
	s_add_u32 s90, s74, 0x10980000
	s_addc_u32 s91, s75, 0
	v_lshl_add_u64 v[156:157], s[90:91], 0, v[166:167]
	v_lshl_add_u64 v[158:159], v[156:157], 0, s[88:89]
	v_mov_b32_e32 v128, 0
	v_mov_b32_e32 v129, 0
	v_mov_b32_e32 v130, 0
	v_mov_b32_e32 v131, 0
	v_mov_b32_e32 v132, 0
	v_mov_b32_e32 v133, 0
	v_mov_b32_e32 v134, 0
	v_mov_b32_e32 v135, 0
	v_mov_b32_e32 v144, 0
	v_mov_b32_e32 v145, 0
	v_mov_b32_e32 v146, 0
	v_mov_b32_e32 v147, 0
	v_mov_b32_e32 v148, 0
	v_mov_b32_e32 v149, 0
	v_mov_b32_e32 v150, 0
	v_mov_b32_e32 v151, 0
	global_load_dwordx4 v[0:3], v[152:153], off
	global_load_dwordx4 v[4:7], v[154:155], off
	global_load_dwordx4 v[8:11], v[156:157], off
	global_load_dwordx4 v[12:15], v[158:159], off
	global_load_dwordx4 v[16:19], v[152:153], off offset:64
	global_load_dwordx4 v[20:23], v[154:155], off offset:64
	global_load_dwordx4 v[24:27], v[156:157], off offset:64
	global_load_dwordx4 v[28:31], v[158:159], off offset:64
	global_load_dwordx4 v[32:35], v[152:153], off offset:128
	global_load_dwordx4 v[36:39], v[154:155], off offset:128
	global_load_dwordx4 v[40:43], v[156:157], off offset:128
	global_load_dwordx4 v[44:47], v[158:159], off offset:128
	global_load_dwordx4 v[48:51], v[152:153], off offset:192
	global_load_dwordx4 v[52:55], v[154:155], off offset:192
	global_load_dwordx4 v[56:59], v[156:157], off offset:192
	global_load_dwordx4 v[60:63], v[158:159], off offset:192
	global_load_dwordx4 v[64:67], v[152:153], off offset:256
	global_load_dwordx4 v[68:71], v[154:155], off offset:256
	global_load_dwordx4 v[72:75], v[156:157], off offset:256
	global_load_dwordx4 v[76:79], v[158:159], off offset:256
	global_load_dwordx4 v[80:83], v[152:153], off offset:320
	global_load_dwordx4 v[84:87], v[154:155], off offset:320
	global_load_dwordx4 v[88:91], v[156:157], off offset:320
	global_load_dwordx4 v[92:95], v[158:159], off offset:320
	global_load_dwordx4 v[96:99], v[152:153], off offset:384
	global_load_dwordx4 v[100:103], v[154:155], off offset:384
	global_load_dwordx4 v[104:107], v[156:157], off offset:384
	global_load_dwordx4 v[108:111], v[158:159], off offset:384
	global_load_dwordx4 v[112:115], v[152:153], off offset:448
	global_load_dwordx4 v[116:119], v[154:155], off offset:448
	global_load_dwordx4 v[120:123], v[156:157], off offset:448
	global_load_dwordx4 v[124:127], v[158:159], off offset:448
	s_waitcnt vmcnt(16)
	v_mfma_f32_16x16x32_bf16 v[128:131], v[0:3], v[8:11], v[128:131]
	v_mfma_f32_16x16x32_bf16 v[132:135], v[4:7], v[8:11], v[132:135]
	v_mfma_f32_16x16x32_bf16 v[144:147], v[0:3], v[12:15], v[144:147]
	v_mfma_f32_16x16x32_bf16 v[148:151], v[4:7], v[12:15], v[148:151]
	v_mfma_f32_16x16x32_bf16 v[128:131], v[16:19], v[24:27], v[128:131]
	v_mfma_f32_16x16x32_bf16 v[132:135], v[20:23], v[24:27], v[132:135]
	v_mfma_f32_16x16x32_bf16 v[144:147], v[16:19], v[28:31], v[144:147]
	v_mfma_f32_16x16x32_bf16 v[148:151], v[20:23], v[28:31], v[148:151]
	v_mfma_f32_16x16x32_bf16 v[128:131], v[32:35], v[40:43], v[128:131]
	v_mfma_f32_16x16x32_bf16 v[132:135], v[36:39], v[40:43], v[132:135]
	v_mfma_f32_16x16x32_bf16 v[144:147], v[32:35], v[44:47], v[144:147]
	v_mfma_f32_16x16x32_bf16 v[148:151], v[36:39], v[44:47], v[148:151]
	v_mfma_f32_16x16x32_bf16 v[128:131], v[48:51], v[56:59], v[128:131]
	v_mfma_f32_16x16x32_bf16 v[132:135], v[52:55], v[56:59], v[132:135]
	v_mfma_f32_16x16x32_bf16 v[144:147], v[48:51], v[60:63], v[144:147]
	v_mfma_f32_16x16x32_bf16 v[148:151], v[52:55], v[60:63], v[148:151]
	global_load_dwordx4 v[0:3], v[152:153], off offset:512
	global_load_dwordx4 v[4:7], v[154:155], off offset:512
	global_load_dwordx4 v[8:11], v[156:157], off offset:512
	global_load_dwordx4 v[12:15], v[158:159], off offset:512
	global_load_dwordx4 v[16:19], v[152:153], off offset:576
	global_load_dwordx4 v[20:23], v[154:155], off offset:576
	global_load_dwordx4 v[24:27], v[156:157], off offset:576
	global_load_dwordx4 v[28:31], v[158:159], off offset:576
	global_load_dwordx4 v[32:35], v[152:153], off offset:640
	global_load_dwordx4 v[36:39], v[154:155], off offset:640
	global_load_dwordx4 v[40:43], v[156:157], off offset:640
	global_load_dwordx4 v[44:47], v[158:159], off offset:640
	s_waitcnt vmcnt(12)
	v_mfma_f32_16x16x32_bf16 v[128:131], v[64:67], v[72:75], v[128:131]
	v_mfma_f32_16x16x32_bf16 v[132:135], v[68:71], v[72:75], v[132:135]
	v_mfma_f32_16x16x32_bf16 v[144:147], v[64:67], v[76:79], v[144:147]
	v_mfma_f32_16x16x32_bf16 v[148:151], v[68:71], v[76:79], v[148:151]
	v_mfma_f32_16x16x32_bf16 v[128:131], v[80:83], v[88:91], v[128:131]
	v_mfma_f32_16x16x32_bf16 v[132:135], v[84:87], v[88:91], v[132:135]
	v_mfma_f32_16x16x32_bf16 v[144:147], v[80:83], v[92:95], v[144:147]
	v_mfma_f32_16x16x32_bf16 v[148:151], v[84:87], v[92:95], v[148:151]
	v_mfma_f32_16x16x32_bf16 v[128:131], v[96:99], v[104:107], v[128:131]
	v_mfma_f32_16x16x32_bf16 v[132:135], v[100:103], v[104:107], v[132:135]
	v_mfma_f32_16x16x32_bf16 v[144:147], v[96:99], v[108:111], v[144:147]
	v_mfma_f32_16x16x32_bf16 v[148:151], v[100:103], v[108:111], v[148:151]
	v_mfma_f32_16x16x32_bf16 v[128:131], v[112:115], v[120:123], v[128:131]
	v_mfma_f32_16x16x32_bf16 v[132:135], v[116:119], v[120:123], v[132:135]
	v_mfma_f32_16x16x32_bf16 v[144:147], v[112:115], v[124:127], v[144:147]
	v_mfma_f32_16x16x32_bf16 v[148:151], v[116:119], v[124:127], v[148:151]
	s_waitcnt vmcnt(0)
	v_mfma_f32_16x16x32_bf16 v[128:131], v[0:3], v[8:11], v[128:131]
	v_mfma_f32_16x16x32_bf16 v[132:135], v[4:7], v[8:11], v[132:135]
	v_mfma_f32_16x16x32_bf16 v[144:147], v[0:3], v[12:15], v[144:147]
	v_mfma_f32_16x16x32_bf16 v[148:151], v[4:7], v[12:15], v[148:151]
	v_mfma_f32_16x16x32_bf16 v[128:131], v[16:19], v[24:27], v[128:131]
	v_mfma_f32_16x16x32_bf16 v[132:135], v[20:23], v[24:27], v[132:135]
	v_mfma_f32_16x16x32_bf16 v[144:147], v[16:19], v[28:31], v[144:147]
	v_mfma_f32_16x16x32_bf16 v[148:151], v[20:23], v[28:31], v[148:151]
	v_mfma_f32_16x16x32_bf16 v[128:131], v[32:35], v[40:43], v[128:131]
	v_mfma_f32_16x16x32_bf16 v[132:135], v[36:39], v[40:43], v[132:135]
	v_mfma_f32_16x16x32_bf16 v[144:147], v[32:35], v[44:47], v[144:147]
	v_mfma_f32_16x16x32_bf16 v[148:151], v[36:39], v[44:47], v[148:151]
	s_nop 7
	s_nop 7
	v_lshlrev_b32_e32 v170, 12, v162
	v_lshl_add_u32 v170, v136, 4, v170
	ds_write_b128 v170, v[128:131]
	ds_write_b128 v170, v[132:135] offset:1024
	ds_write_b128 v170, v[144:147] offset:2048
	ds_write_b128 v170, v[148:151] offset:3072
	s_waitcnt lgkmcnt(0)
	s_barrier
	s_cmp_ge_u32 s80, 4
	s_cbranch_scc1 .Lmg4_end
	s_lshl_b32 s84, s80, 10
	v_lshlrev_b32_e32 v171, 4, v136
	v_add_u32_e32 v171, s84, v171
	ds_read_b128 v[0:3], v171
	ds_read_b128 v[4:7], v171 offset:4096
	ds_read_b128 v[8:11], v171 offset:8192
	ds_read_b128 v[12:15], v171 offset:12288
	ds_read_b128 v[16:19], v171 offset:16384
	ds_read_b128 v[20:23], v171 offset:20480
	ds_read_b128 v[24:27], v171 offset:24576
	ds_read_b128 v[28:31], v171 offset:28672
	s_lshr_b32 s84, s80, 1
	s_lshl_b32 s84, s84, 4
	s_lshl_b32 s85, s81, 5
	s_add_i32 s84, s84, s85
	s_addk_i32 s84, 0x4000
	s_and_b32 s85, s80, 1
	s_lshl_b32 s85, s85, 4
	s_lshl_b32 s83, s82, 5
	s_add_i32 s85, s85, s83
	v_add_u32_e32 v165, s84, v160
	v_lshl_add_u32 v164, v161, 2, s85
	v_lshlrev_b32_e32 v166, 12, v165
	v_lshl_add_u32 v166, v164, 2, v166
	v_mov_b32_e32 v167, 0
	s_add_u32 s86, s74, 0x5000000
	s_addc_u32 s87, s75, 0
	v_lshl_add_u64 v[168:169], s[86:87], 0, v[166:167]
	global_load_dwordx4 v[32:35], v[168:169], off
	v_lshrrev_b32_e32 v172, 1, v166
	v_mov_b32_e32 v173, 0
	s_add_u32 s86, s74, 0x9100000
	s_addc_u32 s87, s75, 0
	v_lshl_add_u64 v[172:173], s[86:87], 0, v[172:173]
	v_lshlrev_b32_e32 v166, 2, v165
	s_add_u32 s86, s74, 0x12bc1800
	s_addc_u32 s87, s75, 0
	v_lshl_add_u64 v[166:167], s[86:87], 0, v[166:167]
	s_waitcnt lgkmcnt(0)
	v_add_f32_e32 v0, v0, v4
	v_add_f32_e32 v1, v1, v5
	v_add_f32_e32 v2, v2, v6
	v_add_f32_e32 v3, v3, v7
	v_add_f32_e32 v0, v0, v8
	v_add_f32_e32 v1, v1, v9
	v_add_f32_e32 v2, v2, v10
	v_add_f32_e32 v3, v3, v11
	v_add_f32_e32 v0, v0, v12
	v_add_f32_e32 v1, v1, v13
	v_add_f32_e32 v2, v2, v14
	v_add_f32_e32 v3, v3, v15
	v_add_f32_e32 v0, v0, v16
	v_add_f32_e32 v1, v1, v17
	v_add_f32_e32 v2, v2, v18
	v_add_f32_e32 v3, v3, v19
	v_add_f32_e32 v0, v0, v20
	v_add_f32_e32 v1, v1, v21
	v_add_f32_e32 v2, v2, v22
	v_add_f32_e32 v3, v3, v23
	v_add_f32_e32 v0, v0, v24
	v_add_f32_e32 v1, v1, v25
	v_add_f32_e32 v2, v2, v26
	v_add_f32_e32 v3, v3, v27
	v_add_f32_e32 v0, v0, v28
	v_add_f32_e32 v1, v1, v29
	v_add_f32_e32 v2, v2, v30
	v_add_f32_e32 v3, v3, v31
	s_waitcnt vmcnt(0)
	v_fma_f32 v32, v0, 0.5, v32
	v_fma_f32 v33, v1, 0.5, v33
	v_fma_f32 v34, v2, 0.5, v34
	v_fma_f32 v35, v3, 0.5, v35
	global_store_dwordx4 v[168:169], v[32:35], off
	v_cvt_pk_bf16_f32 v36, v32, v33
	v_cvt_pk_bf16_f32 v37, v34, v35
	v_mul_f32_e32 v38, v32, v32
	v_fmac_f32_e32 v38, v33, v33
	v_fmac_f32_e32 v38, v34, v34
	v_fmac_f32_e32 v38, v35, v35
	v_xor_b32_e32 v39, 16, v136
	v_lshlrev_b32_e32 v39, 2, v39
	ds_bpermute_b32 v40, v39, v38
	v_xor_b32_e32 v41, 32, v136
	v_lshlrev_b32_e32 v41, 2, v41
	s_waitcnt lgkmcnt(0)
	v_add_f32_e32 v38, v38, v40
	ds_bpermute_b32 v40, v41, v38
	s_waitcnt lgkmcnt(0)
	v_add_f32_e32 v38, v38, v40
	v_cmp_gt_u32_e64 s[82:83], 16, v136
	s_nop 1
	s_and_saveexec_b64 s[84:85], s[82:83]
	global_atomic_add_f32 v[166:167], v38, off
	s_mov_b64 exec, s[84:85]
